# base7 + nt on the f32 input-projection (ZF) stores, consumed two phases later
# speedup vs baseline: 1.0013x; 1.0013x over previous
; __device__ __forceinline__ float sigmoid_fast(float x) { return __builtin_amdgcn_rcpf(1.0f + __expf(-x)); }
;     __device__ __forceinline__ void operator()(EPI_SIG) const {
;     ...
;             for (int m = 0; m < 4; ++m) { float* rowp = C + (size_t)(row0 + ai * 128 + m * 16) * NZF + u.pn * 256 + cc;
; #pragma unroll
;                 for (int bj = 0; bj < 2; ++bj)
; #pragma unroll
;                     for (int n = 0; n < 2; ++n) { f32x4 v = acc[ai][bj][m][n];
;                         if (u.pn < 2) {
; #pragma unroll
;                             for (int t = 0; t < 4; ++t) v[t] = __logf(fmaxf(lbv[bj][n][t] + (1.0f - lbv[bj][n][t]) * sigmoid_fast(v[t]), 1e-30f)); }
;                         if (u.pn < 2 || (bj == 0 && wc == 0 && (n == 0 || fq < 2))) *(f32x4*)(rowp + bj * 128 + n * 16) = v; } }
.LBB0_670:
	v_lshl_add_u32 v170, s42, 8, v160
	s_lshl_b32 s54, s23, 8
	v_mov_b64_e32 v[158:159], s[8:9]
	s_movk_i32 s4, 0xc00
	s_ashr_i32 s55, s54, 31
	v_mad_i64_i32 v[158:159], s[4:5], v170, s4, v[158:159]
	s_or_b64 s[2:3], s[12:13], s[2:3]
	v_lshl_add_u64 v[158:159], s[54:55], 2, v[158:159]
	v_cndmask_b32_e64 v166, 0, 1, s[2:3]
	v_cmp_ne_u32_e64 s[42:43], 1, v166
	s_andn2_b64 vcc, exec, s[2:3]
	v_lshl_add_u64 v[158:159], v[158:159], 0, v[50:51]
	s_cbranch_vccnz .LBB0_672
	flat_store_dwordx4 v[158:159], v[144:147] nt

; __device__ __forceinline__ float sigmoid_fast(float x) { return __builtin_amdgcn_rcpf(1.0f + __expf(-x)); }
;     __device__ __forceinline__ void operator()(EPI_SIG) const {
;     ...
;             for (int m = 0; m < 4; ++m) { float* rowp = C + (size_t)(row0 + ai * 128 + m * 16) * NZF + u.pn * 256 + cc;
; #pragma unroll
;                 for (int bj = 0; bj < 2; ++bj)
; #pragma unroll
;                     for (int n = 0; n < 2; ++n) { f32x4 v = acc[ai][bj][m][n];
;                         if (u.pn < 2) {
; #pragma unroll
;                             for (int t = 0; t < 4; ++t) v[t] = __logf(fmaxf(lbv[bj][n][t] + (1.0f - lbv[bj][n][t]) * sigmoid_fast(v[t]), 1e-30f)); }
;                         if (u.pn < 2 || (bj == 0 && wc == 0 && (n == 0 || fq < 2))) *(f32x4*)(rowp + bj * 128 + n * 16) = v; } }
.LBB0_676:
	s_and_saveexec_b64 s[2:3], s[56:57]
	s_cbranch_execz .LBB0_678
	flat_store_dwordx4 v[158:159], v[140:143] offset:64 nt
.LBB0_678:
	s_or_b64 exec, exec, s[2:3]
	s_and_b64 vcc, exec, s[0:1]
	v_sub_f32_e32 v171, 1.0, v22
	v_sub_f32_e32 v167, 1.0, v23
	v_sub_f32_e32 v147, 1.0, v24
	v_sub_f32_e32 v145, 1.0, v25
	v_sub_f32_e32 v143, 1.0, v14
	v_sub_f32_e32 v142, 1.0, v15
	v_sub_f32_e32 v141, 1.0, v16
	v_sub_f32_e32 v140, 1.0, v17
	s_cbranch_vccnz .LBB0_736
	v_mul_f32_e32 v136, 0xbfb8aa3b, v136
	v_exp_f32_e32 v136, v136
	v_mul_f32_e32 v137, 0xbfb8aa3b, v137
	v_exp_f32_e32 v137, v137
	v_mul_f32_e32 v138, 0xbfb8aa3b, v138
	v_add_f32_e32 v136, 1.0, v136
	v_rcp_f32_e32 v136, v136
	v_add_f32_e32 v137, 1.0, v137
	v_rcp_f32_e32 v137, v137
	v_exp_f32_e32 v138, v138
	v_fma_f32 v136, v136, v171, v22
	v_max_f32_e32 v136, 0xda24260, v136
	v_cmp_gt_f32_e32 vcc, s47, v136
	v_fma_f32 v137, v137, v167, v23
	v_max_f32_e32 v137, 0xda24260, v137
	v_cndmask_b32_e64 v172, 0, 32, vcc
	v_ldexp_f32 v136, v136, v172
	v_log_f32_e32 v136, v136
	v_add_f32_e32 v138, 1.0, v138
	v_rcp_f32_e32 v138, v138
	v_mul_f32_e32 v139, 0xbfb8aa3b, v139
	v_mul_f32_e32 v172, 0x3f317217, v136
	v_fma_f32 v172, v136, s49, -v172
	v_fmac_f32_e32 v172, 0x3377d1cf, v136
	v_fmac_f32_e32 v172, 0x3f317217, v136
	v_cmp_lt_f32_e64 s[4:5], |v136|, s69
	v_fma_f32 v138, v138, v147, v24
	v_max_f32_e32 v138, 0xda24260, v138
	v_cndmask_b32_e64 v136, v136, v172, s[4:5]
	v_cndmask_b32_e32 v172, 0, v231, vcc
	v_cmp_gt_f32_e32 vcc, s47, v137
	v_sub_f32_e32 v136, v136, v172
	v_exp_f32_e32 v139, v139
	v_cndmask_b32_e64 v172, 0, 32, vcc
	v_ldexp_f32 v137, v137, v172
	v_log_f32_e32 v137, v137
	v_add_f32_e32 v139, 1.0, v139
	v_rcp_f32_e32 v139, v139
	v_mul_f32_e32 v132, 0xbfb8aa3b, v132
	v_mul_f32_e32 v172, 0x3f317217, v137
	v_fma_f32 v172, v137, s49, -v172
	v_fmac_f32_e32 v172, 0x3377d1cf, v137
	v_fmac_f32_e32 v172, 0x3f317217, v137
	v_cmp_lt_f32_e64 s[4:5], |v137|, s69
	v_fma_f32 v139, v139, v145, v25
	v_max_f32_e32 v139, 0xda24260, v139
	v_cndmask_b32_e64 v137, v137, v172, s[4:5]
	v_cndmask_b32_e32 v172, 0, v231, vcc
	v_cmp_gt_f32_e32 vcc, s47, v138
	v_sub_f32_e32 v137, v137, v172
	v_exp_f32_e32 v132, v132
	v_cndmask_b32_e64 v172, 0, 32, vcc
	v_ldexp_f32 v138, v138, v172
	v_log_f32_e32 v138, v138
	v_add_f32_e32 v132, 1.0, v132
	v_rcp_f32_e32 v132, v132
	v_mul_f32_e32 v133, 0xbfb8aa3b, v133
	v_mul_f32_e32 v172, 0x3f317217, v138
	v_fma_f32 v172, v138, s49, -v172
	v_fmac_f32_e32 v172, 0x3377d1cf, v138
	v_fmac_f32_e32 v172, 0x3f317217, v138
	v_cmp_lt_f32_e64 s[4:5], |v138|, s69
	v_fma_f32 v132, v132, v143, v14
	v_max_f32_e32 v132, 0xda24260, v132
	v_cndmask_b32_e64 v138, v138, v172, s[4:5]
	v_cndmask_b32_e32 v172, 0, v231, vcc
	v_cmp_gt_f32_e32 vcc, s47, v139
	v_sub_f32_e32 v138, v138, v172
	v_exp_f32_e32 v133, v133
	v_cndmask_b32_e64 v172, 0, 32, vcc
	v_ldexp_f32 v139, v139, v172
	v_log_f32_e32 v139, v139
	v_add_f32_e32 v133, 1.0, v133
	v_rcp_f32_e32 v133, v133
	v_mul_f32_e32 v134, 0xbfb8aa3b, v134
	v_mul_f32_e32 v172, 0x3f317217, v139
	v_fma_f32 v172, v139, s49, -v172
	v_fmac_f32_e32 v172, 0x3377d1cf, v139
	v_fmac_f32_e32 v172, 0x3f317217, v139
	v_cmp_lt_f32_e64 s[4:5], |v139|, s69
	v_fma_f32 v133, v133, v142, v15
	v_max_f32_e32 v133, 0xda24260, v133
	v_cndmask_b32_e64 v139, v139, v172, s[4:5]
	v_cndmask_b32_e32 v172, 0, v231, vcc
	v_sub_f32_e32 v139, v139, v172
	v_cmp_gt_f32_e32 vcc, s47, v132
	flat_store_dwordx4 v[158:159], v[136:139] offset:512 nt
	v_exp_f32_e32 v134, v134
	v_mul_f32_e32 v135, 0xbfb8aa3b, v135
	v_cndmask_b32_e64 v136, 0, 32, vcc
	v_ldexp_f32 v132, v132, v136
	v_log_f32_e32 v132, v132
	v_add_f32_e32 v134, 1.0, v134
	v_rcp_f32_e32 v134, v134
	v_exp_f32_e32 v135, v135
	v_mul_f32_e32 v136, 0x3f317217, v132
	v_fma_f32 v136, v132, s49, -v136
	v_fmac_f32_e32 v136, 0x3377d1cf, v132
	v_fmac_f32_e32 v136, 0x3f317217, v132
	v_cmp_lt_f32_e64 s[4:5], |v132|, s69
	v_fma_f32 v134, v134, v141, v16
	v_max_f32_e32 v134, 0xda24260, v134
	v_cndmask_b32_e64 v132, v132, v136, s[4:5]
	v_cndmask_b32_e32 v136, 0, v231, vcc
	v_cmp_gt_f32_e32 vcc, s47, v133
	v_sub_f32_e32 v132, v132, v136
	v_add_f32_e32 v135, 1.0, v135
	v_cndmask_b32_e64 v136, 0, 32, vcc
	v_ldexp_f32 v133, v133, v136
	v_log_f32_e32 v133, v133
	v_rcp_f32_e32 v135, v135
	v_mul_f32_e32 v136, 0x3f317217, v133
	v_fma_f32 v136, v133, s49, -v136
	v_fmac_f32_e32 v136, 0x3377d1cf, v133
	v_fmac_f32_e32 v136, 0x3f317217, v133
	v_cmp_lt_f32_e64 s[4:5], |v133|, s69
	v_fma_f32 v135, v135, v140, v17
	v_max_f32_e32 v135, 0xda24260, v135
	v_cndmask_b32_e64 v133, v133, v136, s[4:5]
	v_cndmask_b32_e32 v136, 0, v231, vcc
	v_cmp_gt_f32_e32 vcc, s47, v134
	v_sub_f32_e32 v133, v133, v136
	s_nop 0
	v_cndmask_b32_e64 v136, 0, 32, vcc
	v_ldexp_f32 v134, v134, v136
	v_log_f32_e32 v134, v134
	s_nop 0
	v_mul_f32_e32 v136, 0x3f317217, v134
	v_fma_f32 v136, v134, s49, -v136
	v_fmac_f32_e32 v136, 0x3377d1cf, v134
	v_fmac_f32_e32 v136, 0x3f317217, v134
	v_cmp_lt_f32_e64 s[4:5], |v134|, s69
	s_nop 1
	v_cndmask_b32_e64 v134, v134, v136, s[4:5]
	v_cndmask_b32_e32 v136, 0, v231, vcc
	v_cmp_gt_f32_e32 vcc, s47, v135
	v_sub_f32_e32 v134, v134, v136
	s_nop 0
	v_cndmask_b32_e64 v136, 0, 32, vcc
	v_ldexp_f32 v135, v135, v136
	v_log_f32_e32 v135, v135
	s_nop 0
	v_mul_f32_e32 v136, 0x3f317217, v135
	v_fma_f32 v136, v135, s49, -v136
	v_fmac_f32_e32 v136, 0x3377d1cf, v135
	v_fmac_f32_e32 v136, 0x3f317217, v135
	v_cmp_lt_f32_e64 s[4:5], |v135|, s69
	s_nop 1
	v_cndmask_b32_e64 v135, v135, v136, s[4:5]
	v_cndmask_b32_e32 v136, 0, v231, vcc
	v_sub_f32_e32 v135, v135, v136
	flat_store_dwordx4 v[158:159], v[132:135] offset:576 nt
	s_and_b64 vcc, exec, s[40:41]
	s_mov_b64 s[2:3], -1
	s_cbranch_vccz .LBB0_737

; __device__ __forceinline__ float sigmoid_fast(float x) { return __builtin_amdgcn_rcpf(1.0f + __expf(-x)); }
;     __device__ __forceinline__ void operator()(EPI_SIG) const {
;     ...
;             for (int m = 0; m < 4; ++m) { float* rowp = C + (size_t)(row0 + ai * 128 + m * 16) * NZF + u.pn * 256 + cc;
; #pragma unroll
;                 for (int bj = 0; bj < 2; ++bj)
; #pragma unroll
;                     for (int n = 0; n < 2; ++n) { f32x4 v = acc[ai][bj][m][n];
;                         if (u.pn < 2) {
; #pragma unroll
;                             for (int t = 0; t < 4; ++t) v[t] = __logf(fmaxf(lbv[bj][n][t] + (1.0f - lbv[bj][n][t]) * sigmoid_fast(v[t]), 1e-30f)); }
;                         if (u.pn < 2 || (bj == 0 && wc == 0 && (n == 0 || fq < 2))) *(f32x4*)(rowp + bj * 128 + n * 16) = v; } }
.LBB0_682:
	v_or_b32_e32 v134, 16, v170
	v_mov_b64_e32 v[132:133], s[8:9]
	s_movk_i32 s2, 0xc00
	v_mad_i64_i32 v[132:133], s[2:3], v134, s2, v[132:133]
	v_lshl_add_u64 v[132:133], s[54:55], 2, v[132:133]
	s_and_b64 vcc, exec, s[42:43]
	v_lshl_add_u64 v[132:133], v[132:133], 0, v[50:51]
	s_cbranch_vccnz .LBB0_738
	flat_store_dwordx4 v[132:133], v[128:131] nt
	s_and_b64 vcc, exec, s[40:41]
	s_mov_b64 s[2:3], -1
	s_cbranch_vccz .LBB0_739

; __device__ __forceinline__ float sigmoid_fast(float x) { return __builtin_amdgcn_rcpf(1.0f + __expf(-x)); }
;     __device__ __forceinline__ void operator()(EPI_SIG) const {
;     ...
;             for (int m = 0; m < 4; ++m) { float* rowp = C + (size_t)(row0 + ai * 128 + m * 16) * NZF + u.pn * 256 + cc;
; #pragma unroll
;                 for (int bj = 0; bj < 2; ++bj)
; #pragma unroll
;                     for (int n = 0; n < 2; ++n) { f32x4 v = acc[ai][bj][m][n];
;                         if (u.pn < 2) {
; #pragma unroll
;                             for (int t = 0; t < 4; ++t) v[t] = __logf(fmaxf(lbv[bj][n][t] + (1.0f - lbv[bj][n][t]) * sigmoid_fast(v[t]), 1e-30f)); }
;                         if (u.pn < 2 || (bj == 0 && wc == 0 && (n == 0 || fq < 2))) *(f32x4*)(rowp + bj * 128 + n * 16) = v; } }
.LBB0_687:
	v_mul_f32_e32 v120, 0xbfb8aa3b, v120
	v_exp_f32_e32 v120, v120
	v_mul_f32_e32 v121, 0xbfb8aa3b, v121
	v_exp_f32_e32 v121, v121
	v_mul_f32_e32 v122, 0xbfb8aa3b, v122
	v_add_f32_e32 v120, 1.0, v120
	v_rcp_f32_e32 v120, v120
	v_add_f32_e32 v121, 1.0, v121
	v_rcp_f32_e32 v121, v121
	v_exp_f32_e32 v122, v122
	v_fma_f32 v120, v120, v171, v22
	v_max_f32_e32 v120, 0xda24260, v120
	v_cmp_gt_f32_e32 vcc, s47, v120
	v_fma_f32 v121, v121, v167, v23
	v_max_f32_e32 v121, 0xda24260, v121
	v_cndmask_b32_e64 v124, 0, 32, vcc
	v_ldexp_f32 v120, v120, v124
	v_log_f32_e32 v120, v120
	v_add_f32_e32 v122, 1.0, v122
	v_rcp_f32_e32 v122, v122
	v_mul_f32_e32 v123, 0xbfb8aa3b, v123
	v_mul_f32_e32 v124, 0x3f317217, v120
	v_fma_f32 v124, v120, s49, -v124
	v_fmac_f32_e32 v124, 0x3377d1cf, v120
	v_fmac_f32_e32 v124, 0x3f317217, v120
	v_cmp_lt_f32_e64 s[4:5], |v120|, s69
	v_fma_f32 v122, v122, v147, v24
	v_max_f32_e32 v122, 0xda24260, v122
	v_cndmask_b32_e64 v120, v120, v124, s[4:5]
	v_cndmask_b32_e32 v124, 0, v231, vcc
	v_cmp_gt_f32_e32 vcc, s47, v121
	v_sub_f32_e32 v120, v120, v124
	v_exp_f32_e32 v123, v123
	v_cndmask_b32_e64 v124, 0, 32, vcc
	v_ldexp_f32 v121, v121, v124
	v_log_f32_e32 v121, v121
	v_add_f32_e32 v123, 1.0, v123
	v_rcp_f32_e32 v123, v123
	v_mul_f32_e32 v116, 0xbfb8aa3b, v116
	v_mul_f32_e32 v124, 0x3f317217, v121
	v_fma_f32 v124, v121, s49, -v124
	v_fmac_f32_e32 v124, 0x3377d1cf, v121
	v_fmac_f32_e32 v124, 0x3f317217, v121
	v_cmp_lt_f32_e64 s[4:5], |v121|, s69
	v_fma_f32 v123, v123, v145, v25
	v_max_f32_e32 v123, 0xda24260, v123
	v_cndmask_b32_e64 v121, v121, v124, s[4:5]
	v_cndmask_b32_e32 v124, 0, v231, vcc
	v_cmp_gt_f32_e32 vcc, s47, v122
	v_sub_f32_e32 v121, v121, v124
	v_exp_f32_e32 v116, v116
	v_cndmask_b32_e64 v124, 0, 32, vcc
	v_ldexp_f32 v122, v122, v124
	v_log_f32_e32 v122, v122
	v_add_f32_e32 v116, 1.0, v116
	v_rcp_f32_e32 v116, v116
	v_mul_f32_e32 v117, 0xbfb8aa3b, v117
	v_mul_f32_e32 v124, 0x3f317217, v122
	v_fma_f32 v124, v122, s49, -v124
	v_fmac_f32_e32 v124, 0x3377d1cf, v122
	v_fmac_f32_e32 v124, 0x3f317217, v122
	v_cmp_lt_f32_e64 s[4:5], |v122|, s69
	v_fma_f32 v116, v116, v143, v14
	v_max_f32_e32 v116, 0xda24260, v116
	v_cndmask_b32_e64 v122, v122, v124, s[4:5]
	v_cndmask_b32_e32 v124, 0, v231, vcc
	v_cmp_gt_f32_e32 vcc, s47, v123
	v_sub_f32_e32 v122, v122, v124
	v_exp_f32_e32 v117, v117
	v_cndmask_b32_e64 v124, 0, 32, vcc
	v_ldexp_f32 v123, v123, v124
	v_log_f32_e32 v123, v123
	v_add_f32_e32 v117, 1.0, v117
	v_rcp_f32_e32 v117, v117
	v_mul_f32_e32 v118, 0xbfb8aa3b, v118
	v_mul_f32_e32 v124, 0x3f317217, v123
	v_fma_f32 v124, v123, s49, -v124
	v_fmac_f32_e32 v124, 0x3377d1cf, v123
	v_fmac_f32_e32 v124, 0x3f317217, v123
	v_cmp_lt_f32_e64 s[4:5], |v123|, s69
	v_fma_f32 v117, v117, v142, v15
	v_max_f32_e32 v117, 0xda24260, v117
	v_cndmask_b32_e64 v123, v123, v124, s[4:5]
	v_cndmask_b32_e32 v124, 0, v231, vcc
	v_sub_f32_e32 v123, v123, v124
	v_cmp_gt_f32_e32 vcc, s47, v116
	flat_store_dwordx4 v[132:133], v[120:123] offset:512 nt
	v_exp_f32_e32 v118, v118
	v_mul_f32_e32 v119, 0xbfb8aa3b, v119
	v_cndmask_b32_e64 v120, 0, 32, vcc
	v_ldexp_f32 v116, v116, v120
	v_log_f32_e32 v116, v116
	v_add_f32_e32 v118, 1.0, v118
	v_rcp_f32_e32 v118, v118
	v_exp_f32_e32 v119, v119
	v_mul_f32_e32 v120, 0x3f317217, v116
	v_fma_f32 v120, v116, s49, -v120
	v_fmac_f32_e32 v120, 0x3377d1cf, v116
	v_fmac_f32_e32 v120, 0x3f317217, v116
	v_cmp_lt_f32_e64 s[4:5], |v116|, s69
	v_fma_f32 v118, v118, v141, v16
	v_max_f32_e32 v118, 0xda24260, v118
	v_cndmask_b32_e64 v116, v116, v120, s[4:5]
	v_cndmask_b32_e32 v120, 0, v231, vcc
	v_cmp_gt_f32_e32 vcc, s47, v117
	v_sub_f32_e32 v116, v116, v120
	v_add_f32_e32 v119, 1.0, v119
	v_cndmask_b32_e64 v120, 0, 32, vcc
	v_ldexp_f32 v117, v117, v120
	v_log_f32_e32 v117, v117
	v_rcp_f32_e32 v119, v119
	v_mul_f32_e32 v120, 0x3f317217, v117
	v_fma_f32 v120, v117, s49, -v120
	v_fmac_f32_e32 v120, 0x3377d1cf, v117
	v_fmac_f32_e32 v120, 0x3f317217, v117
	v_cmp_lt_f32_e64 s[4:5], |v117|, s69
	v_fma_f32 v119, v119, v140, v17
	v_max_f32_e32 v119, 0xda24260, v119
	v_cndmask_b32_e64 v117, v117, v120, s[4:5]
	v_cndmask_b32_e32 v120, 0, v231, vcc
	v_cmp_gt_f32_e32 vcc, s47, v118
	v_sub_f32_e32 v117, v117, v120
	s_nop 0
	v_cndmask_b32_e64 v120, 0, 32, vcc
	v_ldexp_f32 v118, v118, v120
	v_log_f32_e32 v118, v118
	s_nop 0
	v_mul_f32_e32 v120, 0x3f317217, v118
	v_fma_f32 v120, v118, s49, -v120
	v_fmac_f32_e32 v120, 0x3377d1cf, v118
	v_fmac_f32_e32 v120, 0x3f317217, v118
	v_cmp_lt_f32_e64 s[4:5], |v118|, s69
	s_nop 1
	v_cndmask_b32_e64 v118, v118, v120, s[4:5]
	v_cndmask_b32_e32 v120, 0, v231, vcc
	v_cmp_gt_f32_e32 vcc, s47, v119
	v_sub_f32_e32 v118, v118, v120
	s_nop 0
	v_cndmask_b32_e64 v120, 0, 32, vcc
	v_ldexp_f32 v119, v119, v120
	v_log_f32_e32 v119, v119
	s_nop 0
	v_mul_f32_e32 v120, 0x3f317217, v119
	v_fma_f32 v120, v119, s49, -v120
	v_fmac_f32_e32 v120, 0x3377d1cf, v119
	v_fmac_f32_e32 v120, 0x3f317217, v119
	v_cmp_lt_f32_e64 s[4:5], |v119|, s69
	s_nop 1
	v_cndmask_b32_e64 v119, v119, v120, s[4:5]
	v_cndmask_b32_e32 v120, 0, v231, vcc
	v_sub_f32_e32 v119, v119, v120
	flat_store_dwordx4 v[132:133], v[116:119] offset:576 nt
	s_and_b64 vcc, exec, s[40:41]
	s_mov_b64 s[2:3], -1
	s_cbranch_vccz .LBB0_743

; __device__ __forceinline__ float sigmoid_fast(float x) { return __builtin_amdgcn_rcpf(1.0f + __expf(-x)); }
;     __device__ __forceinline__ void operator()(EPI_SIG) const {
;     ...
;             for (int m = 0; m < 4; ++m) { float* rowp = C + (size_t)(row0 + ai * 128 + m * 16) * NZF + u.pn * 256 + cc;
; #pragma unroll
;                 for (int bj = 0; bj < 2; ++bj)
; #pragma unroll
;                     for (int n = 0; n < 2; ++n) { f32x4 v = acc[ai][bj][m][n];
;                         if (u.pn < 2) {
; #pragma unroll
;                             for (int t = 0; t < 4; ++t) v[t] = __logf(fmaxf(lbv[bj][n][t] + (1.0f - lbv[bj][n][t]) * sigmoid_fast(v[t]), 1e-30f)); }
;                         if (u.pn < 2 || (bj == 0 && wc == 0 && (n == 0 || fq < 2))) *(f32x4*)(rowp + bj * 128 + n * 16) = v; } }
.LBB0_690:
	v_or_b32_e32 v118, 32, v170
	v_mov_b64_e32 v[116:117], s[8:9]
	s_movk_i32 s2, 0xc00
	v_mad_i64_i32 v[116:117], s[2:3], v118, s2, v[116:117]
	v_lshl_add_u64 v[116:117], s[54:55], 2, v[116:117]
	s_and_b64 vcc, exec, s[42:43]
	v_lshl_add_u64 v[116:117], v[116:117], 0, v[50:51]
	s_cbranch_vccnz .LBB0_744
	flat_store_dwordx4 v[116:117], v[112:115] nt
	s_and_b64 vcc, exec, s[40:41]
	s_mov_b64 s[2:3], -1
	s_cbranch_vccz .LBB0_745

; __device__ __forceinline__ float sigmoid_fast(float x) { return __builtin_amdgcn_rcpf(1.0f + __expf(-x)); }
;     __device__ __forceinline__ void operator()(EPI_SIG) const {
;     ...
;             for (int m = 0; m < 4; ++m) { float* rowp = C + (size_t)(row0 + ai * 128 + m * 16) * NZF + u.pn * 256 + cc;
; #pragma unroll
;                 for (int bj = 0; bj < 2; ++bj)
; #pragma unroll
;                     for (int n = 0; n < 2; ++n) { f32x4 v = acc[ai][bj][m][n];
;                         if (u.pn < 2) {
; #pragma unroll
;                             for (int t = 0; t < 4; ++t) v[t] = __logf(fmaxf(lbv[bj][n][t] + (1.0f - lbv[bj][n][t]) * sigmoid_fast(v[t]), 1e-30f)); }
;                         if (u.pn < 2 || (bj == 0 && wc == 0 && (n == 0 || fq < 2))) *(f32x4*)(rowp + bj * 128 + n * 16) = v; } }
.LBB0_695:
	v_mul_f32_e32 v104, 0xbfb8aa3b, v104
	v_exp_f32_e32 v104, v104
	v_mul_f32_e32 v105, 0xbfb8aa3b, v105
	v_exp_f32_e32 v105, v105
	v_mul_f32_e32 v106, 0xbfb8aa3b, v106
	v_add_f32_e32 v104, 1.0, v104
	v_rcp_f32_e32 v104, v104
	v_add_f32_e32 v105, 1.0, v105
	v_rcp_f32_e32 v105, v105
	v_exp_f32_e32 v106, v106
	v_fma_f32 v104, v104, v171, v22
	v_max_f32_e32 v104, 0xda24260, v104
	v_cmp_gt_f32_e32 vcc, s47, v104
	v_fma_f32 v105, v105, v167, v23
	v_max_f32_e32 v105, 0xda24260, v105
	v_cndmask_b32_e64 v108, 0, 32, vcc
	v_ldexp_f32 v104, v104, v108
	v_log_f32_e32 v104, v104
	v_add_f32_e32 v106, 1.0, v106
	v_rcp_f32_e32 v106, v106
	v_mul_f32_e32 v107, 0xbfb8aa3b, v107
	v_mul_f32_e32 v108, 0x3f317217, v104
	v_fma_f32 v108, v104, s49, -v108
	v_fmac_f32_e32 v108, 0x3377d1cf, v104
	v_fmac_f32_e32 v108, 0x3f317217, v104
	v_cmp_lt_f32_e64 s[4:5], |v104|, s69
	v_fma_f32 v106, v106, v147, v24
	v_max_f32_e32 v106, 0xda24260, v106
	v_cndmask_b32_e64 v104, v104, v108, s[4:5]
	v_cndmask_b32_e32 v108, 0, v231, vcc
	v_cmp_gt_f32_e32 vcc, s47, v105
	v_sub_f32_e32 v104, v104, v108
	v_exp_f32_e32 v107, v107
	v_cndmask_b32_e64 v108, 0, 32, vcc
	v_ldexp_f32 v105, v105, v108
	v_log_f32_e32 v105, v105
	v_add_f32_e32 v107, 1.0, v107
	v_rcp_f32_e32 v107, v107
	v_mul_f32_e32 v100, 0xbfb8aa3b, v100
	v_mul_f32_e32 v108, 0x3f317217, v105
	v_fma_f32 v108, v105, s49, -v108
	v_fmac_f32_e32 v108, 0x3377d1cf, v105
	v_fmac_f32_e32 v108, 0x3f317217, v105
	v_cmp_lt_f32_e64 s[4:5], |v105|, s69
	v_fma_f32 v107, v107, v145, v25
	v_max_f32_e32 v107, 0xda24260, v107
	v_cndmask_b32_e64 v105, v105, v108, s[4:5]
	v_cndmask_b32_e32 v108, 0, v231, vcc
	v_cmp_gt_f32_e32 vcc, s47, v106
	v_sub_f32_e32 v105, v105, v108
	v_exp_f32_e32 v100, v100
	v_cndmask_b32_e64 v108, 0, 32, vcc
	v_ldexp_f32 v106, v106, v108
	v_log_f32_e32 v106, v106
	v_add_f32_e32 v100, 1.0, v100
	v_rcp_f32_e32 v100, v100
	v_mul_f32_e32 v101, 0xbfb8aa3b, v101
	v_mul_f32_e32 v108, 0x3f317217, v106
	v_fma_f32 v108, v106, s49, -v108
	v_fmac_f32_e32 v108, 0x3377d1cf, v106
	v_fmac_f32_e32 v108, 0x3f317217, v106
	v_cmp_lt_f32_e64 s[4:5], |v106|, s69
	v_fma_f32 v100, v100, v143, v14
	v_max_f32_e32 v100, 0xda24260, v100
	v_cndmask_b32_e64 v106, v106, v108, s[4:5]
	v_cndmask_b32_e32 v108, 0, v231, vcc
	v_cmp_gt_f32_e32 vcc, s47, v107
	v_sub_f32_e32 v106, v106, v108
	v_exp_f32_e32 v101, v101
	v_cndmask_b32_e64 v108, 0, 32, vcc
	v_ldexp_f32 v107, v107, v108
	v_log_f32_e32 v107, v107
	v_add_f32_e32 v101, 1.0, v101
	v_rcp_f32_e32 v101, v101
	v_mul_f32_e32 v102, 0xbfb8aa3b, v102
	v_mul_f32_e32 v108, 0x3f317217, v107
	v_fma_f32 v108, v107, s49, -v108
	v_fmac_f32_e32 v108, 0x3377d1cf, v107
	v_fmac_f32_e32 v108, 0x3f317217, v107
	v_cmp_lt_f32_e64 s[4:5], |v107|, s69
	v_fma_f32 v101, v101, v142, v15
	v_max_f32_e32 v101, 0xda24260, v101
	v_cndmask_b32_e64 v107, v107, v108, s[4:5]
	v_cndmask_b32_e32 v108, 0, v231, vcc
	v_sub_f32_e32 v107, v107, v108
	v_cmp_gt_f32_e32 vcc, s47, v100
	flat_store_dwordx4 v[116:117], v[104:107] offset:512 nt
	v_exp_f32_e32 v102, v102
	v_mul_f32_e32 v103, 0xbfb8aa3b, v103
	v_cndmask_b32_e64 v104, 0, 32, vcc
	v_ldexp_f32 v100, v100, v104
	v_log_f32_e32 v100, v100
	v_add_f32_e32 v102, 1.0, v102
	v_rcp_f32_e32 v102, v102
	v_exp_f32_e32 v103, v103
	v_mul_f32_e32 v104, 0x3f317217, v100
	v_fma_f32 v104, v100, s49, -v104
	v_fmac_f32_e32 v104, 0x3377d1cf, v100
	v_fmac_f32_e32 v104, 0x3f317217, v100
	v_cmp_lt_f32_e64 s[4:5], |v100|, s69
	v_fma_f32 v102, v102, v141, v16
	v_max_f32_e32 v102, 0xda24260, v102
	v_cndmask_b32_e64 v100, v100, v104, s[4:5]
	v_cndmask_b32_e32 v104, 0, v231, vcc
	v_cmp_gt_f32_e32 vcc, s47, v101
	v_sub_f32_e32 v100, v100, v104
	v_add_f32_e32 v103, 1.0, v103
	v_cndmask_b32_e64 v104, 0, 32, vcc
	v_ldexp_f32 v101, v101, v104
	v_log_f32_e32 v101, v101
	v_rcp_f32_e32 v103, v103
	v_mul_f32_e32 v104, 0x3f317217, v101
	v_fma_f32 v104, v101, s49, -v104
	v_fmac_f32_e32 v104, 0x3377d1cf, v101
	v_fmac_f32_e32 v104, 0x3f317217, v101
	v_cmp_lt_f32_e64 s[4:5], |v101|, s69
	v_fma_f32 v103, v103, v140, v17
	v_max_f32_e32 v103, 0xda24260, v103
	v_cndmask_b32_e64 v101, v101, v104, s[4:5]
	v_cndmask_b32_e32 v104, 0, v231, vcc
	v_cmp_gt_f32_e32 vcc, s47, v102
	v_sub_f32_e32 v101, v101, v104
	s_nop 0
	v_cndmask_b32_e64 v104, 0, 32, vcc
	v_ldexp_f32 v102, v102, v104
	v_log_f32_e32 v102, v102
	s_nop 0
	v_mul_f32_e32 v104, 0x3f317217, v102
	v_fma_f32 v104, v102, s49, -v104
	v_fmac_f32_e32 v104, 0x3377d1cf, v102
	v_fmac_f32_e32 v104, 0x3f317217, v102
	v_cmp_lt_f32_e64 s[4:5], |v102|, s69
	s_nop 1
	v_cndmask_b32_e64 v102, v102, v104, s[4:5]
	v_cndmask_b32_e32 v104, 0, v231, vcc
	v_cmp_gt_f32_e32 vcc, s47, v103
	v_sub_f32_e32 v102, v102, v104
	s_nop 0
	v_cndmask_b32_e64 v104, 0, 32, vcc
	v_ldexp_f32 v103, v103, v104
	v_log_f32_e32 v103, v103
	s_nop 0
	v_mul_f32_e32 v104, 0x3f317217, v103
	v_fma_f32 v104, v103, s49, -v104
	v_fmac_f32_e32 v104, 0x3377d1cf, v103
	v_fmac_f32_e32 v104, 0x3f317217, v103
	v_cmp_lt_f32_e64 s[4:5], |v103|, s69
	s_nop 1
	v_cndmask_b32_e64 v103, v103, v104, s[4:5]
	v_cndmask_b32_e32 v104, 0, v231, vcc
	v_sub_f32_e32 v103, v103, v104
	flat_store_dwordx4 v[116:117], v[100:103] offset:576 nt
	s_and_b64 vcc, exec, s[40:41]
	s_mov_b64 s[2:3], -1
	s_cbranch_vccz .LBB0_749

; __device__ __forceinline__ float sigmoid_fast(float x) { return __builtin_amdgcn_rcpf(1.0f + __expf(-x)); }
;     __device__ __forceinline__ void operator()(EPI_SIG) const {
;     ...
;             for (int m = 0; m < 4; ++m) { float* rowp = C + (size_t)(row0 + ai * 128 + m * 16) * NZF + u.pn * 256 + cc;
; #pragma unroll
;                 for (int bj = 0; bj < 2; ++bj)
; #pragma unroll
;                     for (int n = 0; n < 2; ++n) { f32x4 v = acc[ai][bj][m][n];
;                         if (u.pn < 2) {
; #pragma unroll
;                             for (int t = 0; t < 4; ++t) v[t] = __logf(fmaxf(lbv[bj][n][t] + (1.0f - lbv[bj][n][t]) * sigmoid_fast(v[t]), 1e-30f)); }
;                         if (u.pn < 2 || (bj == 0 && wc == 0 && (n == 0 || fq < 2))) *(f32x4*)(rowp + bj * 128 + n * 16) = v; } }
.LBB0_698:
	v_or_b32_e32 v102, 48, v170
	v_mov_b64_e32 v[100:101], s[8:9]
	s_movk_i32 s2, 0xc00
	v_mad_i64_i32 v[100:101], s[2:3], v102, s2, v[100:101]
	v_lshl_add_u64 v[100:101], s[54:55], 2, v[100:101]
	s_and_b64 vcc, exec, s[42:43]
	v_lshl_add_u64 v[100:101], v[100:101], 0, v[50:51]
	s_cbranch_vccnz .LBB0_750
	flat_store_dwordx4 v[100:101], v[96:99] nt
	s_and_b64 vcc, exec, s[40:41]
	s_mov_b64 s[2:3], -1
	s_cbranch_vccz .LBB0_751

; __device__ __forceinline__ float sigmoid_fast(float x) { return __builtin_amdgcn_rcpf(1.0f + __expf(-x)); }
;     __device__ __forceinline__ void operator()(EPI_SIG) const {
;     ...
;             for (int m = 0; m < 4; ++m) { float* rowp = C + (size_t)(row0 + ai * 128 + m * 16) * NZF + u.pn * 256 + cc;
; #pragma unroll
;                 for (int bj = 0; bj < 2; ++bj)
; #pragma unroll
;                     for (int n = 0; n < 2; ++n) { f32x4 v = acc[ai][bj][m][n];
;                         if (u.pn < 2) {
; #pragma unroll
;                             for (int t = 0; t < 4; ++t) v[t] = __logf(fmaxf(lbv[bj][n][t] + (1.0f - lbv[bj][n][t]) * sigmoid_fast(v[t]), 1e-30f)); }
;                         if (u.pn < 2 || (bj == 0 && wc == 0 && (n == 0 || fq < 2))) *(f32x4*)(rowp + bj * 128 + n * 16) = v; } }
.LBB0_703:
	v_mul_f32_e32 v88, 0xbfb8aa3b, v88
	v_exp_f32_e32 v88, v88
	v_mul_f32_e32 v89, 0xbfb8aa3b, v89
	v_exp_f32_e32 v89, v89
	v_mul_f32_e32 v90, 0xbfb8aa3b, v90
	v_add_f32_e32 v88, 1.0, v88
	v_rcp_f32_e32 v88, v88
	v_add_f32_e32 v89, 1.0, v89
	v_rcp_f32_e32 v89, v89
	v_exp_f32_e32 v90, v90
	v_fma_f32 v88, v88, v171, v22
	v_max_f32_e32 v88, 0xda24260, v88
	v_cmp_gt_f32_e32 vcc, s47, v88
	v_fma_f32 v89, v89, v167, v23
	v_max_f32_e32 v89, 0xda24260, v89
	v_cndmask_b32_e64 v92, 0, 32, vcc
	v_ldexp_f32 v88, v88, v92
	v_log_f32_e32 v88, v88
	v_add_f32_e32 v90, 1.0, v90
	v_rcp_f32_e32 v90, v90
	v_mul_f32_e32 v91, 0xbfb8aa3b, v91
	v_mul_f32_e32 v92, 0x3f317217, v88
	v_fma_f32 v92, v88, s49, -v92
	v_fmac_f32_e32 v92, 0x3377d1cf, v88
	v_fmac_f32_e32 v92, 0x3f317217, v88
	v_cmp_lt_f32_e64 s[4:5], |v88|, s69
	v_fma_f32 v90, v90, v147, v24
	v_max_f32_e32 v90, 0xda24260, v90
	v_cndmask_b32_e64 v88, v88, v92, s[4:5]
	v_cndmask_b32_e32 v92, 0, v231, vcc
	v_cmp_gt_f32_e32 vcc, s47, v89
	v_sub_f32_e32 v88, v88, v92
	v_exp_f32_e32 v91, v91
	v_cndmask_b32_e64 v92, 0, 32, vcc
	v_ldexp_f32 v89, v89, v92
	v_log_f32_e32 v89, v89
	v_add_f32_e32 v91, 1.0, v91
	v_rcp_f32_e32 v91, v91
	v_mul_f32_e32 v84, 0xbfb8aa3b, v84
	v_mul_f32_e32 v92, 0x3f317217, v89
	v_fma_f32 v92, v89, s49, -v92
	v_fmac_f32_e32 v92, 0x3377d1cf, v89
	v_fmac_f32_e32 v92, 0x3f317217, v89
	v_cmp_lt_f32_e64 s[4:5], |v89|, s69
	v_fma_f32 v91, v91, v145, v25
	v_max_f32_e32 v91, 0xda24260, v91
	v_cndmask_b32_e64 v89, v89, v92, s[4:5]
	v_cndmask_b32_e32 v92, 0, v231, vcc
	v_cmp_gt_f32_e32 vcc, s47, v90
	v_sub_f32_e32 v89, v89, v92
	v_exp_f32_e32 v84, v84
	v_cndmask_b32_e64 v92, 0, 32, vcc
	v_ldexp_f32 v90, v90, v92
	v_log_f32_e32 v90, v90
	v_add_f32_e32 v84, 1.0, v84
	v_rcp_f32_e32 v84, v84
	v_mul_f32_e32 v85, 0xbfb8aa3b, v85
	v_mul_f32_e32 v92, 0x3f317217, v90
	v_fma_f32 v92, v90, s49, -v92
	v_fmac_f32_e32 v92, 0x3377d1cf, v90
	v_fmac_f32_e32 v92, 0x3f317217, v90
	v_cmp_lt_f32_e64 s[4:5], |v90|, s69
	v_fma_f32 v84, v84, v143, v14
	v_max_f32_e32 v84, 0xda24260, v84
	v_cndmask_b32_e64 v90, v90, v92, s[4:5]
	v_cndmask_b32_e32 v92, 0, v231, vcc
	v_cmp_gt_f32_e32 vcc, s47, v91
	v_sub_f32_e32 v90, v90, v92
	v_exp_f32_e32 v85, v85
	v_cndmask_b32_e64 v92, 0, 32, vcc
	v_ldexp_f32 v91, v91, v92
	v_log_f32_e32 v91, v91
	v_add_f32_e32 v85, 1.0, v85
	v_rcp_f32_e32 v85, v85
	v_mul_f32_e32 v86, 0xbfb8aa3b, v86
	v_mul_f32_e32 v92, 0x3f317217, v91
	v_fma_f32 v92, v91, s49, -v92
	v_fmac_f32_e32 v92, 0x3377d1cf, v91
	v_fmac_f32_e32 v92, 0x3f317217, v91
	v_cmp_lt_f32_e64 s[4:5], |v91|, s69
	v_fma_f32 v85, v85, v142, v15
	v_max_f32_e32 v85, 0xda24260, v85
	v_cndmask_b32_e64 v91, v91, v92, s[4:5]
	v_cndmask_b32_e32 v92, 0, v231, vcc
	v_sub_f32_e32 v91, v91, v92
	v_cmp_gt_f32_e32 vcc, s47, v84
	flat_store_dwordx4 v[100:101], v[88:91] offset:512 nt
	v_exp_f32_e32 v86, v86
	v_mul_f32_e32 v87, 0xbfb8aa3b, v87
	v_cndmask_b32_e64 v88, 0, 32, vcc
	v_ldexp_f32 v84, v84, v88
	v_log_f32_e32 v84, v84
	v_add_f32_e32 v86, 1.0, v86
	v_rcp_f32_e32 v86, v86
	v_exp_f32_e32 v87, v87
	v_mul_f32_e32 v88, 0x3f317217, v84
	v_fma_f32 v88, v84, s49, -v88
	v_fmac_f32_e32 v88, 0x3377d1cf, v84
	v_fmac_f32_e32 v88, 0x3f317217, v84
	v_cmp_lt_f32_e64 s[4:5], |v84|, s69
	v_fma_f32 v86, v86, v141, v16
	v_max_f32_e32 v86, 0xda24260, v86
	v_cndmask_b32_e64 v84, v84, v88, s[4:5]
	v_cndmask_b32_e32 v88, 0, v231, vcc
	v_cmp_gt_f32_e32 vcc, s47, v85
	v_sub_f32_e32 v84, v84, v88
	v_add_f32_e32 v87, 1.0, v87
	v_cndmask_b32_e64 v88, 0, 32, vcc
	v_ldexp_f32 v85, v85, v88
	v_log_f32_e32 v85, v85
	v_rcp_f32_e32 v87, v87
	v_mul_f32_e32 v88, 0x3f317217, v85
	v_fma_f32 v88, v85, s49, -v88
	v_fmac_f32_e32 v88, 0x3377d1cf, v85
	v_fmac_f32_e32 v88, 0x3f317217, v85
	v_cmp_lt_f32_e64 s[4:5], |v85|, s69
	v_fma_f32 v87, v87, v140, v17
	v_max_f32_e32 v87, 0xda24260, v87
	v_cndmask_b32_e64 v85, v85, v88, s[4:5]
	v_cndmask_b32_e32 v88, 0, v231, vcc
	v_cmp_gt_f32_e32 vcc, s47, v86
	v_sub_f32_e32 v85, v85, v88
	s_nop 0
	v_cndmask_b32_e64 v88, 0, 32, vcc
	v_ldexp_f32 v86, v86, v88
	v_log_f32_e32 v86, v86
	s_nop 0
	v_mul_f32_e32 v88, 0x3f317217, v86
	v_fma_f32 v88, v86, s49, -v88
	v_fmac_f32_e32 v88, 0x3377d1cf, v86
	v_fmac_f32_e32 v88, 0x3f317217, v86
	v_cmp_lt_f32_e64 s[4:5], |v86|, s69
	s_nop 1
	v_cndmask_b32_e64 v86, v86, v88, s[4:5]
	v_cndmask_b32_e32 v88, 0, v231, vcc
	v_cmp_gt_f32_e32 vcc, s47, v87
	v_sub_f32_e32 v86, v86, v88
	s_nop 0
	v_cndmask_b32_e64 v88, 0, 32, vcc
	v_ldexp_f32 v87, v87, v88
	v_log_f32_e32 v87, v87
	s_nop 0
	v_mul_f32_e32 v88, 0x3f317217, v87
	v_fma_f32 v88, v87, s49, -v88
	v_fmac_f32_e32 v88, 0x3377d1cf, v87
	v_fmac_f32_e32 v88, 0x3f317217, v87
	v_cmp_lt_f32_e64 s[4:5], |v87|, s69
	s_nop 1
	v_cndmask_b32_e64 v87, v87, v88, s[4:5]
	v_cndmask_b32_e32 v88, 0, v231, vcc
	v_sub_f32_e32 v87, v87, v88
	flat_store_dwordx4 v[100:101], v[84:87] offset:576 nt
	s_and_b64 vcc, exec, s[40:41]
	s_mov_b64 s[2:3], -1
	s_cbranch_vccz .LBB0_755

; __device__ __forceinline__ float sigmoid_fast(float x) { return __builtin_amdgcn_rcpf(1.0f + __expf(-x)); }
;     __device__ __forceinline__ void operator()(EPI_SIG) const {
;     ...
;             for (int m = 0; m < 4; ++m) { float* rowp = C + (size_t)(row0 + ai * 128 + m * 16) * NZF + u.pn * 256 + cc;
; #pragma unroll
;                 for (int bj = 0; bj < 2; ++bj)
; #pragma unroll
;                     for (int n = 0; n < 2; ++n) { f32x4 v = acc[ai][bj][m][n];
;                         if (u.pn < 2) {
; #pragma unroll
;                             for (int t = 0; t < 4; ++t) v[t] = __logf(fmaxf(lbv[bj][n][t] + (1.0f - lbv[bj][n][t]) * sigmoid_fast(v[t]), 1e-30f)); }
;                         if (u.pn < 2 || (bj == 0 && wc == 0 && (n == 0 || fq < 2))) *(f32x4*)(rowp + bj * 128 + n * 16) = v; } }
.LBB0_706:
	v_add_u32_e32 v86, 0x80, v170
	v_mov_b64_e32 v[84:85], s[8:9]
	s_movk_i32 s2, 0xc00
	v_mad_i64_i32 v[84:85], s[2:3], v86, s2, v[84:85]
	v_lshl_add_u64 v[84:85], s[54:55], 2, v[84:85]
	s_and_b64 vcc, exec, s[42:43]
	v_lshl_add_u64 v[84:85], v[84:85], 0, v[50:51]
	s_cbranch_vccnz .LBB0_756
	flat_store_dwordx4 v[84:85], v[80:83] nt
	s_and_b64 vcc, exec, s[40:41]
	s_mov_b64 s[2:3], -1
	s_cbranch_vccz .LBB0_757

; __device__ __forceinline__ float sigmoid_fast(float x) { return __builtin_amdgcn_rcpf(1.0f + __expf(-x)); }
;     __device__ __forceinline__ void operator()(EPI_SIG) const {
;     ...
;             for (int m = 0; m < 4; ++m) { float* rowp = C + (size_t)(row0 + ai * 128 + m * 16) * NZF + u.pn * 256 + cc;
; #pragma unroll
;                 for (int bj = 0; bj < 2; ++bj)
; #pragma unroll
;                     for (int n = 0; n < 2; ++n) { f32x4 v = acc[ai][bj][m][n];
;                         if (u.pn < 2) {
; #pragma unroll
;                             for (int t = 0; t < 4; ++t) v[t] = __logf(fmaxf(lbv[bj][n][t] + (1.0f - lbv[bj][n][t]) * sigmoid_fast(v[t]), 1e-30f)); }
;                         if (u.pn < 2 || (bj == 0 && wc == 0 && (n == 0 || fq < 2))) *(f32x4*)(rowp + bj * 128 + n * 16) = v; } }
.LBB0_711:
	v_mul_f32_e32 v72, 0xbfb8aa3b, v72
	v_exp_f32_e32 v72, v72
	v_mul_f32_e32 v73, 0xbfb8aa3b, v73
	v_exp_f32_e32 v73, v73
	v_mul_f32_e32 v74, 0xbfb8aa3b, v74
	v_add_f32_e32 v72, 1.0, v72
	v_rcp_f32_e32 v72, v72
	v_add_f32_e32 v73, 1.0, v73
	v_rcp_f32_e32 v73, v73
	v_exp_f32_e32 v74, v74
	v_fma_f32 v72, v72, v171, v22
	v_max_f32_e32 v72, 0xda24260, v72
	v_cmp_gt_f32_e32 vcc, s47, v72
	v_fma_f32 v73, v73, v167, v23
	v_max_f32_e32 v73, 0xda24260, v73
	v_cndmask_b32_e64 v76, 0, 32, vcc
	v_ldexp_f32 v72, v72, v76
	v_log_f32_e32 v72, v72
	v_add_f32_e32 v74, 1.0, v74
	v_rcp_f32_e32 v74, v74
	v_mul_f32_e32 v75, 0xbfb8aa3b, v75
	v_mul_f32_e32 v76, 0x3f317217, v72
	v_fma_f32 v76, v72, s49, -v76
	v_fmac_f32_e32 v76, 0x3377d1cf, v72
	v_fmac_f32_e32 v76, 0x3f317217, v72
	v_cmp_lt_f32_e64 s[4:5], |v72|, s69
	v_fma_f32 v74, v74, v147, v24
	v_max_f32_e32 v74, 0xda24260, v74
	v_cndmask_b32_e64 v72, v72, v76, s[4:5]
	v_cndmask_b32_e32 v76, 0, v231, vcc
	v_cmp_gt_f32_e32 vcc, s47, v73
	v_sub_f32_e32 v72, v72, v76
	v_exp_f32_e32 v75, v75
	v_cndmask_b32_e64 v76, 0, 32, vcc
	v_ldexp_f32 v73, v73, v76
	v_log_f32_e32 v73, v73
	v_add_f32_e32 v75, 1.0, v75
	v_rcp_f32_e32 v75, v75
	v_mul_f32_e32 v68, 0xbfb8aa3b, v68
	v_mul_f32_e32 v76, 0x3f317217, v73
	v_fma_f32 v76, v73, s49, -v76
	v_fmac_f32_e32 v76, 0x3377d1cf, v73
	v_fmac_f32_e32 v76, 0x3f317217, v73
	v_cmp_lt_f32_e64 s[4:5], |v73|, s69
	v_fma_f32 v75, v75, v145, v25
	v_max_f32_e32 v75, 0xda24260, v75
	v_cndmask_b32_e64 v73, v73, v76, s[4:5]
	v_cndmask_b32_e32 v76, 0, v231, vcc
	v_cmp_gt_f32_e32 vcc, s47, v74
	v_sub_f32_e32 v73, v73, v76
	v_exp_f32_e32 v68, v68
	v_cndmask_b32_e64 v76, 0, 32, vcc
	v_ldexp_f32 v74, v74, v76
	v_log_f32_e32 v74, v74
	v_add_f32_e32 v68, 1.0, v68
	v_rcp_f32_e32 v68, v68
	v_mul_f32_e32 v69, 0xbfb8aa3b, v69
	v_mul_f32_e32 v76, 0x3f317217, v74
	v_fma_f32 v76, v74, s49, -v76
	v_fmac_f32_e32 v76, 0x3377d1cf, v74
	v_fmac_f32_e32 v76, 0x3f317217, v74
	v_cmp_lt_f32_e64 s[4:5], |v74|, s69
	v_fma_f32 v68, v68, v143, v14
	v_max_f32_e32 v68, 0xda24260, v68
	v_cndmask_b32_e64 v74, v74, v76, s[4:5]
	v_cndmask_b32_e32 v76, 0, v231, vcc
	v_cmp_gt_f32_e32 vcc, s47, v75
	v_sub_f32_e32 v74, v74, v76
	v_exp_f32_e32 v69, v69
	v_cndmask_b32_e64 v76, 0, 32, vcc
	v_ldexp_f32 v75, v75, v76
	v_log_f32_e32 v75, v75
	v_add_f32_e32 v69, 1.0, v69
	v_rcp_f32_e32 v69, v69
	v_mul_f32_e32 v70, 0xbfb8aa3b, v70
	v_mul_f32_e32 v76, 0x3f317217, v75
	v_fma_f32 v76, v75, s49, -v76
	v_fmac_f32_e32 v76, 0x3377d1cf, v75
	v_fmac_f32_e32 v76, 0x3f317217, v75
	v_cmp_lt_f32_e64 s[4:5], |v75|, s69
	v_fma_f32 v69, v69, v142, v15
	v_max_f32_e32 v69, 0xda24260, v69
	v_cndmask_b32_e64 v75, v75, v76, s[4:5]
	v_cndmask_b32_e32 v76, 0, v231, vcc
	v_sub_f32_e32 v75, v75, v76
	v_cmp_gt_f32_e32 vcc, s47, v68
	flat_store_dwordx4 v[84:85], v[72:75] offset:512 nt
	v_exp_f32_e32 v70, v70
	v_mul_f32_e32 v71, 0xbfb8aa3b, v71
	v_cndmask_b32_e64 v72, 0, 32, vcc
	v_ldexp_f32 v68, v68, v72
	v_log_f32_e32 v68, v68
	v_add_f32_e32 v70, 1.0, v70
	v_rcp_f32_e32 v70, v70
	v_exp_f32_e32 v71, v71
	v_mul_f32_e32 v72, 0x3f317217, v68
	v_fma_f32 v72, v68, s49, -v72
	v_fmac_f32_e32 v72, 0x3377d1cf, v68
	v_fmac_f32_e32 v72, 0x3f317217, v68
	v_cmp_lt_f32_e64 s[4:5], |v68|, s69
	v_fma_f32 v70, v70, v141, v16
	v_max_f32_e32 v70, 0xda24260, v70
	v_cndmask_b32_e64 v68, v68, v72, s[4:5]
	v_cndmask_b32_e32 v72, 0, v231, vcc
	v_cmp_gt_f32_e32 vcc, s47, v69
	v_sub_f32_e32 v68, v68, v72
	v_add_f32_e32 v71, 1.0, v71
	v_cndmask_b32_e64 v72, 0, 32, vcc
	v_ldexp_f32 v69, v69, v72
	v_log_f32_e32 v69, v69
	v_rcp_f32_e32 v71, v71
	v_mul_f32_e32 v72, 0x3f317217, v69
	v_fma_f32 v72, v69, s49, -v72
	v_fmac_f32_e32 v72, 0x3377d1cf, v69
	v_fmac_f32_e32 v72, 0x3f317217, v69
	v_cmp_lt_f32_e64 s[4:5], |v69|, s69
	v_fma_f32 v71, v71, v140, v17
	v_max_f32_e32 v71, 0xda24260, v71
	v_cndmask_b32_e64 v69, v69, v72, s[4:5]
	v_cndmask_b32_e32 v72, 0, v231, vcc
	v_cmp_gt_f32_e32 vcc, s47, v70
	v_sub_f32_e32 v69, v69, v72
	s_nop 0
	v_cndmask_b32_e64 v72, 0, 32, vcc
	v_ldexp_f32 v70, v70, v72
	v_log_f32_e32 v70, v70
	s_nop 0
	v_mul_f32_e32 v72, 0x3f317217, v70
	v_fma_f32 v72, v70, s49, -v72
	v_fmac_f32_e32 v72, 0x3377d1cf, v70
	v_fmac_f32_e32 v72, 0x3f317217, v70
	v_cmp_lt_f32_e64 s[4:5], |v70|, s69
	s_nop 1
	v_cndmask_b32_e64 v70, v70, v72, s[4:5]
	v_cndmask_b32_e32 v72, 0, v231, vcc
	v_cmp_gt_f32_e32 vcc, s47, v71
	v_sub_f32_e32 v70, v70, v72
	s_nop 0
	v_cndmask_b32_e64 v72, 0, 32, vcc
	v_ldexp_f32 v71, v71, v72
	v_log_f32_e32 v71, v71
	s_nop 0
	v_mul_f32_e32 v72, 0x3f317217, v71
	v_fma_f32 v72, v71, s49, -v72
	v_fmac_f32_e32 v72, 0x3377d1cf, v71
	v_fmac_f32_e32 v72, 0x3f317217, v71
	v_cmp_lt_f32_e64 s[4:5], |v71|, s69
	s_nop 1
	v_cndmask_b32_e64 v71, v71, v72, s[4:5]
	v_cndmask_b32_e32 v72, 0, v231, vcc
	v_sub_f32_e32 v71, v71, v72
	flat_store_dwordx4 v[84:85], v[68:71] offset:576 nt
	s_and_b64 vcc, exec, s[40:41]
	s_mov_b64 s[2:3], -1
	s_cbranch_vccz .LBB0_761

; __device__ __forceinline__ float sigmoid_fast(float x) { return __builtin_amdgcn_rcpf(1.0f + __expf(-x)); }
;     __device__ __forceinline__ void operator()(EPI_SIG) const {
;     ...
;             for (int m = 0; m < 4; ++m) { float* rowp = C + (size_t)(row0 + ai * 128 + m * 16) * NZF + u.pn * 256 + cc;
; #pragma unroll
;                 for (int bj = 0; bj < 2; ++bj)
; #pragma unroll
;                     for (int n = 0; n < 2; ++n) { f32x4 v = acc[ai][bj][m][n];
;                         if (u.pn < 2) {
; #pragma unroll
;                             for (int t = 0; t < 4; ++t) v[t] = __logf(fmaxf(lbv[bj][n][t] + (1.0f - lbv[bj][n][t]) * sigmoid_fast(v[t]), 1e-30f)); }
;                         if (u.pn < 2 || (bj == 0 && wc == 0 && (n == 0 || fq < 2))) *(f32x4*)(rowp + bj * 128 + n * 16) = v; } }
.LBB0_714:
	v_add_u32_e32 v70, 0x90, v170
	v_mov_b64_e32 v[68:69], s[8:9]
	s_movk_i32 s2, 0xc00
	v_mad_i64_i32 v[68:69], s[2:3], v70, s2, v[68:69]
	v_lshl_add_u64 v[68:69], s[54:55], 2, v[68:69]
	s_and_b64 vcc, exec, s[42:43]
	v_lshl_add_u64 v[68:69], v[68:69], 0, v[50:51]
	s_cbranch_vccnz .LBB0_762
	flat_store_dwordx4 v[68:69], v[64:67] nt
	s_and_b64 vcc, exec, s[40:41]
	s_mov_b64 s[2:3], -1
	s_cbranch_vccz .LBB0_763

; __device__ __forceinline__ float sigmoid_fast(float x) { return __builtin_amdgcn_rcpf(1.0f + __expf(-x)); }
;     __device__ __forceinline__ void operator()(EPI_SIG) const {
;     ...
;             for (int m = 0; m < 4; ++m) { float* rowp = C + (size_t)(row0 + ai * 128 + m * 16) * NZF + u.pn * 256 + cc;
; #pragma unroll
;                 for (int bj = 0; bj < 2; ++bj)
; #pragma unroll
;                     for (int n = 0; n < 2; ++n) { f32x4 v = acc[ai][bj][m][n];
;                         if (u.pn < 2) {
; #pragma unroll
;                             for (int t = 0; t < 4; ++t) v[t] = __logf(fmaxf(lbv[bj][n][t] + (1.0f - lbv[bj][n][t]) * sigmoid_fast(v[t]), 1e-30f)); }
;                         if (u.pn < 2 || (bj == 0 && wc == 0 && (n == 0 || fq < 2))) *(f32x4*)(rowp + bj * 128 + n * 16) = v; } }
.LBB0_719:
	v_mul_f32_e32 v56, 0xbfb8aa3b, v56
	v_exp_f32_e32 v56, v56
	v_mul_f32_e32 v57, 0xbfb8aa3b, v57
	v_exp_f32_e32 v57, v57
	v_mul_f32_e32 v58, 0xbfb8aa3b, v58
	v_add_f32_e32 v56, 1.0, v56
	v_rcp_f32_e32 v56, v56
	v_add_f32_e32 v57, 1.0, v57
	v_rcp_f32_e32 v57, v57
	v_exp_f32_e32 v58, v58
	v_fma_f32 v56, v56, v171, v22
	v_max_f32_e32 v56, 0xda24260, v56
	v_cmp_gt_f32_e32 vcc, s47, v56
	v_fma_f32 v57, v57, v167, v23
	v_max_f32_e32 v57, 0xda24260, v57
	v_cndmask_b32_e64 v60, 0, 32, vcc
	v_ldexp_f32 v56, v56, v60
	v_log_f32_e32 v56, v56
	v_add_f32_e32 v58, 1.0, v58
	v_rcp_f32_e32 v58, v58
	v_mul_f32_e32 v59, 0xbfb8aa3b, v59
	v_mul_f32_e32 v60, 0x3f317217, v56
	v_fma_f32 v60, v56, s49, -v60
	v_fmac_f32_e32 v60, 0x3377d1cf, v56
	v_fmac_f32_e32 v60, 0x3f317217, v56
	v_cmp_lt_f32_e64 s[4:5], |v56|, s69
	v_fma_f32 v58, v58, v147, v24
	v_max_f32_e32 v58, 0xda24260, v58
	v_cndmask_b32_e64 v56, v56, v60, s[4:5]
	v_cndmask_b32_e32 v60, 0, v231, vcc
	v_cmp_gt_f32_e32 vcc, s47, v57
	v_sub_f32_e32 v56, v56, v60
	v_exp_f32_e32 v59, v59
	v_cndmask_b32_e64 v60, 0, 32, vcc
	v_ldexp_f32 v57, v57, v60
	v_log_f32_e32 v57, v57
	v_add_f32_e32 v59, 1.0, v59
	v_rcp_f32_e32 v59, v59
	v_mul_f32_e32 v52, 0xbfb8aa3b, v52
	v_mul_f32_e32 v60, 0x3f317217, v57
	v_fma_f32 v60, v57, s49, -v60
	v_fmac_f32_e32 v60, 0x3377d1cf, v57
	v_fmac_f32_e32 v60, 0x3f317217, v57
	v_cmp_lt_f32_e64 s[4:5], |v57|, s69
	v_fma_f32 v59, v59, v145, v25
	v_max_f32_e32 v59, 0xda24260, v59
	v_cndmask_b32_e64 v57, v57, v60, s[4:5]
	v_cndmask_b32_e32 v60, 0, v231, vcc
	v_cmp_gt_f32_e32 vcc, s47, v58
	v_sub_f32_e32 v57, v57, v60
	v_exp_f32_e32 v52, v52
	v_cndmask_b32_e64 v60, 0, 32, vcc
	v_ldexp_f32 v58, v58, v60
	v_log_f32_e32 v58, v58
	v_add_f32_e32 v52, 1.0, v52
	v_rcp_f32_e32 v52, v52
	v_mul_f32_e32 v53, 0xbfb8aa3b, v53
	v_mul_f32_e32 v60, 0x3f317217, v58
	v_fma_f32 v60, v58, s49, -v60
	v_fmac_f32_e32 v60, 0x3377d1cf, v58
	v_fmac_f32_e32 v60, 0x3f317217, v58
	v_cmp_lt_f32_e64 s[4:5], |v58|, s69
	v_fma_f32 v52, v52, v143, v14
	v_max_f32_e32 v52, 0xda24260, v52
	v_cndmask_b32_e64 v58, v58, v60, s[4:5]
	v_cndmask_b32_e32 v60, 0, v231, vcc
	v_cmp_gt_f32_e32 vcc, s47, v59
	v_sub_f32_e32 v58, v58, v60
	v_exp_f32_e32 v53, v53
	v_cndmask_b32_e64 v60, 0, 32, vcc
	v_ldexp_f32 v59, v59, v60
	v_log_f32_e32 v59, v59
	v_add_f32_e32 v53, 1.0, v53
	v_rcp_f32_e32 v53, v53
	v_mul_f32_e32 v54, 0xbfb8aa3b, v54
	v_mul_f32_e32 v60, 0x3f317217, v59
	v_fma_f32 v60, v59, s49, -v60
	v_fmac_f32_e32 v60, 0x3377d1cf, v59
	v_fmac_f32_e32 v60, 0x3f317217, v59
	v_cmp_lt_f32_e64 s[4:5], |v59|, s69
	v_fma_f32 v53, v53, v142, v15
	v_max_f32_e32 v53, 0xda24260, v53
	v_cndmask_b32_e64 v59, v59, v60, s[4:5]
	v_cndmask_b32_e32 v60, 0, v231, vcc
	v_sub_f32_e32 v59, v59, v60
	v_cmp_gt_f32_e32 vcc, s47, v52
	flat_store_dwordx4 v[68:69], v[56:59] offset:512 nt
	v_exp_f32_e32 v54, v54
	v_mul_f32_e32 v55, 0xbfb8aa3b, v55
	v_cndmask_b32_e64 v56, 0, 32, vcc
	v_ldexp_f32 v52, v52, v56
	v_log_f32_e32 v52, v52
	v_add_f32_e32 v54, 1.0, v54
	v_rcp_f32_e32 v54, v54
	v_exp_f32_e32 v55, v55
	v_mul_f32_e32 v56, 0x3f317217, v52
	v_fma_f32 v56, v52, s49, -v56
	v_fmac_f32_e32 v56, 0x3377d1cf, v52
	v_fmac_f32_e32 v56, 0x3f317217, v52
	v_cmp_lt_f32_e64 s[4:5], |v52|, s69
	v_fma_f32 v54, v54, v141, v16
	v_max_f32_e32 v54, 0xda24260, v54
	v_cndmask_b32_e64 v52, v52, v56, s[4:5]
	v_cndmask_b32_e32 v56, 0, v231, vcc
	v_cmp_gt_f32_e32 vcc, s47, v53
	v_sub_f32_e32 v52, v52, v56
	v_add_f32_e32 v55, 1.0, v55
	v_cndmask_b32_e64 v56, 0, 32, vcc
	v_ldexp_f32 v53, v53, v56
	v_log_f32_e32 v53, v53
	v_rcp_f32_e32 v55, v55
	v_mul_f32_e32 v56, 0x3f317217, v53
	v_fma_f32 v56, v53, s49, -v56
	v_fmac_f32_e32 v56, 0x3377d1cf, v53
	v_fmac_f32_e32 v56, 0x3f317217, v53
	v_cmp_lt_f32_e64 s[4:5], |v53|, s69
	v_fma_f32 v55, v55, v140, v17
	v_max_f32_e32 v55, 0xda24260, v55
	v_cndmask_b32_e64 v53, v53, v56, s[4:5]
	v_cndmask_b32_e32 v56, 0, v231, vcc
	v_cmp_gt_f32_e32 vcc, s47, v54
	v_sub_f32_e32 v53, v53, v56
	s_nop 0
	v_cndmask_b32_e64 v56, 0, 32, vcc
	v_ldexp_f32 v54, v54, v56
	v_log_f32_e32 v54, v54
	s_nop 0
	v_mul_f32_e32 v56, 0x3f317217, v54
	v_fma_f32 v56, v54, s49, -v56
	v_fmac_f32_e32 v56, 0x3377d1cf, v54
	v_fmac_f32_e32 v56, 0x3f317217, v54
	v_cmp_lt_f32_e64 s[4:5], |v54|, s69
	s_nop 1
	v_cndmask_b32_e64 v54, v54, v56, s[4:5]
	v_cndmask_b32_e32 v56, 0, v231, vcc
	v_cmp_gt_f32_e32 vcc, s47, v55
	v_sub_f32_e32 v54, v54, v56
	s_nop 0
	v_cndmask_b32_e64 v56, 0, 32, vcc
	v_ldexp_f32 v55, v55, v56
	v_log_f32_e32 v55, v55
	s_nop 0
	v_mul_f32_e32 v56, 0x3f317217, v55
	v_fma_f32 v56, v55, s49, -v56
	v_fmac_f32_e32 v56, 0x3377d1cf, v55
	v_fmac_f32_e32 v56, 0x3f317217, v55
	v_cmp_lt_f32_e64 s[4:5], |v55|, s69
	s_nop 1
	v_cndmask_b32_e64 v55, v55, v56, s[4:5]
	v_cndmask_b32_e32 v56, 0, v231, vcc
	v_sub_f32_e32 v55, v55, v56
	flat_store_dwordx4 v[68:69], v[52:55] offset:576 nt
	s_and_b64 vcc, exec, s[40:41]
	s_mov_b64 s[2:3], -1
	s_cbranch_vccz .LBB0_767

; __device__ __forceinline__ float sigmoid_fast(float x) { return __builtin_amdgcn_rcpf(1.0f + __expf(-x)); }
;     __device__ __forceinline__ void operator()(EPI_SIG) const {
;     ...
;             for (int m = 0; m < 4; ++m) { float* rowp = C + (size_t)(row0 + ai * 128 + m * 16) * NZF + u.pn * 256 + cc;
; #pragma unroll
;                 for (int bj = 0; bj < 2; ++bj)
; #pragma unroll
;                     for (int n = 0; n < 2; ++n) { f32x4 v = acc[ai][bj][m][n];
;                         if (u.pn < 2) {
; #pragma unroll
;                             for (int t = 0; t < 4; ++t) v[t] = __logf(fmaxf(lbv[bj][n][t] + (1.0f - lbv[bj][n][t]) * sigmoid_fast(v[t]), 1e-30f)); }
;                         if (u.pn < 2 || (bj == 0 && wc == 0 && (n == 0 || fq < 2))) *(f32x4*)(rowp + bj * 128 + n * 16) = v; } }
.LBB0_722:
	v_add_u32_e32 v54, 0xa0, v170
	v_mov_b64_e32 v[52:53], s[8:9]
	s_movk_i32 s2, 0xc00
	v_mad_i64_i32 v[52:53], s[2:3], v54, s2, v[52:53]
	v_lshl_add_u64 v[52:53], s[54:55], 2, v[52:53]
	s_and_b64 vcc, exec, s[42:43]
	v_lshl_add_u64 v[52:53], v[52:53], 0, v[50:51]
	s_cbranch_vccnz .LBB0_768
	flat_store_dwordx4 v[52:53], v[46:49] nt
	s_and_b64 vcc, exec, s[40:41]
	s_mov_b64 s[2:3], -1
	s_cbranch_vccz .LBB0_769

; __device__ __forceinline__ float sigmoid_fast(float x) { return __builtin_amdgcn_rcpf(1.0f + __expf(-x)); }
;     __device__ __forceinline__ void operator()(EPI_SIG) const {
;     ...
;             for (int m = 0; m < 4; ++m) { float* rowp = C + (size_t)(row0 + ai * 128 + m * 16) * NZF + u.pn * 256 + cc;
; #pragma unroll
;                 for (int bj = 0; bj < 2; ++bj)
; #pragma unroll
;                     for (int n = 0; n < 2; ++n) { f32x4 v = acc[ai][bj][m][n];
;                         if (u.pn < 2) {
; #pragma unroll
;                             for (int t = 0; t < 4; ++t) v[t] = __logf(fmaxf(lbv[bj][n][t] + (1.0f - lbv[bj][n][t]) * sigmoid_fast(v[t]), 1e-30f)); }
;                         if (u.pn < 2 || (bj == 0 && wc == 0 && (n == 0 || fq < 2))) *(f32x4*)(rowp + bj * 128 + n * 16) = v; } }
.LBB0_727:
	v_mul_f32_e32 v38, 0xbfb8aa3b, v38
	v_exp_f32_e32 v38, v38
	v_mul_f32_e32 v39, 0xbfb8aa3b, v39
	v_exp_f32_e32 v39, v39
	v_mul_f32_e32 v40, 0xbfb8aa3b, v40
	v_add_f32_e32 v38, 1.0, v38
	v_rcp_f32_e32 v38, v38
	v_add_f32_e32 v39, 1.0, v39
	v_rcp_f32_e32 v39, v39
	v_exp_f32_e32 v40, v40
	v_fma_f32 v38, v38, v171, v22
	v_max_f32_e32 v38, 0xda24260, v38
	v_cmp_gt_f32_e32 vcc, s47, v38
	v_fma_f32 v39, v39, v167, v23
	v_max_f32_e32 v39, 0xda24260, v39
	v_cndmask_b32_e64 v42, 0, 32, vcc
	v_ldexp_f32 v38, v38, v42
	v_log_f32_e32 v38, v38
	v_add_f32_e32 v40, 1.0, v40
	v_rcp_f32_e32 v40, v40
	v_mul_f32_e32 v41, 0xbfb8aa3b, v41
	v_mul_f32_e32 v42, 0x3f317217, v38
	v_fma_f32 v42, v38, s49, -v42
	v_fmac_f32_e32 v42, 0x3377d1cf, v38
	v_fmac_f32_e32 v42, 0x3f317217, v38
	v_cmp_lt_f32_e64 s[4:5], |v38|, s69
	v_fma_f32 v40, v40, v147, v24
	v_max_f32_e32 v40, 0xda24260, v40
	v_cndmask_b32_e64 v38, v38, v42, s[4:5]
	v_cndmask_b32_e32 v42, 0, v231, vcc
	v_cmp_gt_f32_e32 vcc, s47, v39
	v_sub_f32_e32 v38, v38, v42
	v_exp_f32_e32 v41, v41
	v_cndmask_b32_e64 v42, 0, 32, vcc
	v_ldexp_f32 v39, v39, v42
	v_log_f32_e32 v39, v39
	v_add_f32_e32 v41, 1.0, v41
	v_rcp_f32_e32 v41, v41
	v_mul_f32_e32 v30, 0xbfb8aa3b, v30
	v_mul_f32_e32 v42, 0x3f317217, v39
	v_fma_f32 v42, v39, s49, -v42
	v_fmac_f32_e32 v42, 0x3377d1cf, v39
	v_fmac_f32_e32 v42, 0x3f317217, v39
	v_cmp_lt_f32_e64 s[4:5], |v39|, s69
	v_fma_f32 v41, v41, v145, v25
	v_max_f32_e32 v41, 0xda24260, v41
	v_cndmask_b32_e64 v39, v39, v42, s[4:5]
	v_cndmask_b32_e32 v42, 0, v231, vcc
	v_cmp_gt_f32_e32 vcc, s47, v40
	v_sub_f32_e32 v39, v39, v42
	v_exp_f32_e32 v30, v30
	v_cndmask_b32_e64 v42, 0, 32, vcc
	v_ldexp_f32 v40, v40, v42
	v_log_f32_e32 v40, v40
	v_add_f32_e32 v30, 1.0, v30
	v_rcp_f32_e32 v30, v30
	v_mul_f32_e32 v31, 0xbfb8aa3b, v31
	v_mul_f32_e32 v42, 0x3f317217, v40
	v_fma_f32 v42, v40, s49, -v42
	v_fmac_f32_e32 v42, 0x3377d1cf, v40
	v_fmac_f32_e32 v42, 0x3f317217, v40
	v_cmp_lt_f32_e64 s[4:5], |v40|, s69
	v_fma_f32 v30, v30, v143, v14
	v_max_f32_e32 v30, 0xda24260, v30
	v_cndmask_b32_e64 v40, v40, v42, s[4:5]
	v_cndmask_b32_e32 v42, 0, v231, vcc
	v_cmp_gt_f32_e32 vcc, s47, v41
	v_sub_f32_e32 v40, v40, v42
	v_exp_f32_e32 v31, v31
	v_cndmask_b32_e64 v42, 0, 32, vcc
	v_ldexp_f32 v41, v41, v42
	v_log_f32_e32 v41, v41
	v_add_f32_e32 v31, 1.0, v31
	v_rcp_f32_e32 v31, v31
	v_mul_f32_e32 v32, 0xbfb8aa3b, v32
	v_mul_f32_e32 v42, 0x3f317217, v41
	v_fma_f32 v42, v41, s49, -v42
	v_fmac_f32_e32 v42, 0x3377d1cf, v41
	v_fmac_f32_e32 v42, 0x3f317217, v41
	v_cmp_lt_f32_e64 s[4:5], |v41|, s69
	v_fma_f32 v31, v31, v142, v15
	v_max_f32_e32 v31, 0xda24260, v31
	v_cndmask_b32_e64 v41, v41, v42, s[4:5]
	v_cndmask_b32_e32 v42, 0, v231, vcc
	v_sub_f32_e32 v41, v41, v42
	v_cmp_gt_f32_e32 vcc, s47, v30
	flat_store_dwordx4 v[52:53], v[38:41] offset:512 nt
	v_exp_f32_e32 v32, v32
	v_mul_f32_e32 v33, 0xbfb8aa3b, v33
	v_cndmask_b32_e64 v38, 0, 32, vcc
	v_ldexp_f32 v30, v30, v38
	v_log_f32_e32 v30, v30
	v_add_f32_e32 v32, 1.0, v32
	v_rcp_f32_e32 v32, v32
	v_exp_f32_e32 v33, v33
	v_mul_f32_e32 v38, 0x3f317217, v30
	v_fma_f32 v38, v30, s49, -v38
	v_fmac_f32_e32 v38, 0x3377d1cf, v30
	v_fmac_f32_e32 v38, 0x3f317217, v30
	v_cmp_lt_f32_e64 s[4:5], |v30|, s69
	v_fma_f32 v32, v32, v141, v16
	v_max_f32_e32 v32, 0xda24260, v32
	v_cndmask_b32_e64 v30, v30, v38, s[4:5]
	v_cndmask_b32_e32 v38, 0, v231, vcc
	v_cmp_gt_f32_e32 vcc, s47, v31
	v_sub_f32_e32 v30, v30, v38
	v_add_f32_e32 v33, 1.0, v33
	v_cndmask_b32_e64 v38, 0, 32, vcc
	v_ldexp_f32 v31, v31, v38
	v_log_f32_e32 v31, v31
	v_rcp_f32_e32 v33, v33
	v_mul_f32_e32 v38, 0x3f317217, v31
	v_fma_f32 v38, v31, s49, -v38
	v_fmac_f32_e32 v38, 0x3377d1cf, v31
	v_fmac_f32_e32 v38, 0x3f317217, v31
	v_cmp_lt_f32_e64 s[4:5], |v31|, s69
	v_fma_f32 v33, v33, v140, v17
	v_max_f32_e32 v33, 0xda24260, v33
	v_cndmask_b32_e64 v31, v31, v38, s[4:5]
	v_cndmask_b32_e32 v38, 0, v231, vcc
	v_cmp_gt_f32_e32 vcc, s47, v32
	v_sub_f32_e32 v31, v31, v38
	s_nop 0
	v_cndmask_b32_e64 v38, 0, 32, vcc
	v_ldexp_f32 v32, v32, v38
	v_log_f32_e32 v32, v32
	s_nop 0
	v_mul_f32_e32 v38, 0x3f317217, v32
	v_fma_f32 v38, v32, s49, -v38
	v_fmac_f32_e32 v38, 0x3377d1cf, v32
	v_fmac_f32_e32 v38, 0x3f317217, v32
	v_cmp_lt_f32_e64 s[4:5], |v32|, s69
	s_nop 1
	v_cndmask_b32_e64 v32, v32, v38, s[4:5]
	v_cndmask_b32_e32 v38, 0, v231, vcc
	v_cmp_gt_f32_e32 vcc, s47, v33
	v_sub_f32_e32 v32, v32, v38
	s_nop 0
	v_cndmask_b32_e64 v38, 0, 32, vcc
	v_ldexp_f32 v33, v33, v38
	v_log_f32_e32 v33, v33
	s_nop 0
	v_mul_f32_e32 v38, 0x3f317217, v33
	v_fma_f32 v38, v33, s49, -v38
	v_fmac_f32_e32 v38, 0x3377d1cf, v33
	v_fmac_f32_e32 v38, 0x3f317217, v33
	v_cmp_lt_f32_e64 s[4:5], |v33|, s69
	s_nop 1
	v_cndmask_b32_e64 v33, v33, v38, s[4:5]
	v_cndmask_b32_e32 v38, 0, v231, vcc
	v_sub_f32_e32 v33, v33, v38
	flat_store_dwordx4 v[52:53], v[30:33] offset:576 nt
	s_and_b64 vcc, exec, s[40:41]
	s_mov_b64 s[2:3], -1
	s_cbranch_vccz .LBB0_773

; __device__ __forceinline__ float sigmoid_fast(float x) { return __builtin_amdgcn_rcpf(1.0f + __expf(-x)); }
;     __device__ __forceinline__ void operator()(EPI_SIG) const {
;     ...
;             for (int m = 0; m < 4; ++m) { float* rowp = C + (size_t)(row0 + ai * 128 + m * 16) * NZF + u.pn * 256 + cc;
; #pragma unroll
;                 for (int bj = 0; bj < 2; ++bj)
; #pragma unroll
;                     for (int n = 0; n < 2; ++n) { f32x4 v = acc[ai][bj][m][n];
;                         if (u.pn < 2) {
; #pragma unroll
;                             for (int t = 0; t < 4; ++t) v[t] = __logf(fmaxf(lbv[bj][n][t] + (1.0f - lbv[bj][n][t]) * sigmoid_fast(v[t]), 1e-30f)); }
;                         if (u.pn < 2 || (bj == 0 && wc == 0 && (n == 0 || fq < 2))) *(f32x4*)(rowp + bj * 128 + n * 16) = v; } }
.LBB0_730:
	v_add_u32_e32 v32, 0xb0, v170
	v_mov_b64_e32 v[30:31], s[8:9]
	s_movk_i32 s2, 0xc00
	v_mad_i64_i32 v[30:31], s[2:3], v32, s2, v[30:31]
	v_lshl_add_u64 v[30:31], s[54:55], 2, v[30:31]
	s_and_b64 vcc, exec, s[42:43]
	v_lshl_add_u64 v[30:31], v[30:31], 0, v[50:51]
	s_cbranch_vccnz .LBB0_774
	flat_store_dwordx4 v[30:31], v[18:21] nt
	s_and_b64 vcc, exec, s[40:41]
	s_mov_b64 s[2:3], -1
	s_cbranch_vccz .LBB0_775

; __device__ __forceinline__ float sigmoid_fast(float x) { return __builtin_amdgcn_rcpf(1.0f + __expf(-x)); }
;     __device__ __forceinline__ void operator()(EPI_SIG) const {
;     ...
;             for (int m = 0; m < 4; ++m) { float* rowp = C + (size_t)(row0 + ai * 128 + m * 16) * NZF + u.pn * 256 + cc;
; #pragma unroll
;                 for (int bj = 0; bj < 2; ++bj)
; #pragma unroll
;                     for (int n = 0; n < 2; ++n) { f32x4 v = acc[ai][bj][m][n];
;                         if (u.pn < 2) {
; #pragma unroll
;                             for (int t = 0; t < 4; ++t) v[t] = __logf(fmaxf(lbv[bj][n][t] + (1.0f - lbv[bj][n][t]) * sigmoid_fast(v[t]), 1e-30f)); }
;                         if (u.pn < 2 || (bj == 0 && wc == 0 && (n == 0 || fq < 2))) *(f32x4*)(rowp + bj * 128 + n * 16) = v; } }
.LBB0_735:
	v_mul_f32_e32 v6, 0xbfb8aa3b, v6
	v_exp_f32_e32 v6, v6
	v_mul_f32_e32 v7, 0xbfb8aa3b, v7
	v_exp_f32_e32 v7, v7
	v_mul_f32_e32 v8, 0xbfb8aa3b, v8
	v_add_f32_e32 v6, 1.0, v6
	v_rcp_f32_e32 v6, v6
	v_add_f32_e32 v7, 1.0, v7
	v_rcp_f32_e32 v7, v7
	v_exp_f32_e32 v8, v8
	v_fmac_f32_e32 v22, v6, v171
	v_max_f32_e32 v6, 0xda24260, v22
	v_cmp_gt_f32_e32 vcc, s47, v6
	v_fmac_f32_e32 v23, v7, v167
	v_max_f32_e32 v7, 0xda24260, v23
	v_cndmask_b32_e64 v10, 0, 32, vcc
	v_ldexp_f32 v6, v6, v10
	v_log_f32_e32 v6, v6
	v_add_f32_e32 v8, 1.0, v8
	v_rcp_f32_e32 v8, v8
	v_mul_f32_e32 v9, 0xbfb8aa3b, v9
	v_mul_f32_e32 v10, 0x3f317217, v6
	v_fma_f32 v10, v6, s49, -v10
	v_fmac_f32_e32 v10, 0x3377d1cf, v6
	v_fmac_f32_e32 v10, 0x3f317217, v6
	v_cmp_lt_f32_e64 s[0:1], |v6|, s69
	v_fmac_f32_e32 v24, v8, v147
	v_max_f32_e32 v8, 0xda24260, v24
	v_cndmask_b32_e64 v6, v6, v10, s[0:1]
	v_cndmask_b32_e32 v10, 0, v231, vcc
	v_cmp_gt_f32_e32 vcc, s47, v7
	v_sub_f32_e32 v6, v6, v10
	v_exp_f32_e32 v9, v9
	v_cndmask_b32_e64 v10, 0, 32, vcc
	v_ldexp_f32 v7, v7, v10
	v_log_f32_e32 v7, v7
	v_add_f32_e32 v9, 1.0, v9
	v_rcp_f32_e32 v9, v9
	v_mul_f32_e32 v2, 0xbfb8aa3b, v2
	v_mul_f32_e32 v10, 0x3f317217, v7
	v_fma_f32 v10, v7, s49, -v10
	v_fmac_f32_e32 v10, 0x3377d1cf, v7
	v_fmac_f32_e32 v10, 0x3f317217, v7
	v_cmp_lt_f32_e64 s[0:1], |v7|, s69
	v_fmac_f32_e32 v25, v9, v145
	v_max_f32_e32 v9, 0xda24260, v25
	v_cndmask_b32_e64 v7, v7, v10, s[0:1]
	v_cndmask_b32_e32 v10, 0, v231, vcc
	v_cmp_gt_f32_e32 vcc, s47, v8
	v_sub_f32_e32 v7, v7, v10
	v_exp_f32_e32 v2, v2
	v_cndmask_b32_e64 v10, 0, 32, vcc
	v_ldexp_f32 v8, v8, v10
	v_log_f32_e32 v8, v8
	v_add_f32_e32 v2, 1.0, v2
	v_rcp_f32_e32 v2, v2
	v_mul_f32_e32 v3, 0xbfb8aa3b, v3
	v_mul_f32_e32 v10, 0x3f317217, v8
	v_fma_f32 v10, v8, s49, -v10
	v_fmac_f32_e32 v10, 0x3377d1cf, v8
	v_fmac_f32_e32 v10, 0x3f317217, v8
	v_cmp_lt_f32_e64 s[0:1], |v8|, s69
	v_fmac_f32_e32 v14, v2, v143
	v_max_f32_e32 v2, 0xda24260, v14
	v_cndmask_b32_e64 v8, v8, v10, s[0:1]
	v_cndmask_b32_e32 v10, 0, v231, vcc
	v_cmp_gt_f32_e32 vcc, s47, v9
	v_sub_f32_e32 v8, v8, v10
	v_exp_f32_e32 v3, v3
	v_cndmask_b32_e64 v10, 0, 32, vcc
	v_ldexp_f32 v9, v9, v10
	v_log_f32_e32 v9, v9
	v_add_f32_e32 v3, 1.0, v3
	v_rcp_f32_e32 v3, v3
	v_mul_f32_e32 v4, 0xbfb8aa3b, v4
	v_mul_f32_e32 v10, 0x3f317217, v9
	v_fma_f32 v10, v9, s49, -v10
	v_fmac_f32_e32 v10, 0x3377d1cf, v9
	v_fmac_f32_e32 v10, 0x3f317217, v9
	v_cmp_lt_f32_e64 s[0:1], |v9|, s69
	v_fmac_f32_e32 v15, v3, v142
	v_max_f32_e32 v3, 0xda24260, v15
	v_cndmask_b32_e64 v9, v9, v10, s[0:1]
	v_cndmask_b32_e32 v10, 0, v231, vcc
	v_sub_f32_e32 v9, v9, v10
	v_cmp_gt_f32_e32 vcc, s47, v2
	flat_store_dwordx4 v[30:31], v[6:9] offset:512 nt
	v_exp_f32_e32 v4, v4
	v_mul_f32_e32 v5, 0xbfb8aa3b, v5
	v_cndmask_b32_e64 v6, 0, 32, vcc
	v_ldexp_f32 v2, v2, v6
	v_log_f32_e32 v2, v2
	v_add_f32_e32 v4, 1.0, v4
	v_rcp_f32_e32 v4, v4
	v_exp_f32_e32 v5, v5
	v_mul_f32_e32 v6, 0x3f317217, v2
	v_fma_f32 v6, v2, s49, -v6
	v_fmac_f32_e32 v6, 0x3377d1cf, v2
	v_fmac_f32_e32 v6, 0x3f317217, v2
	v_cmp_lt_f32_e64 s[0:1], |v2|, s69
	v_fmac_f32_e32 v16, v4, v141
	v_max_f32_e32 v4, 0xda24260, v16
	v_cndmask_b32_e64 v2, v2, v6, s[0:1]
	v_cndmask_b32_e32 v6, 0, v231, vcc
	v_cmp_gt_f32_e32 vcc, s47, v3
	v_sub_f32_e32 v2, v2, v6
	v_add_f32_e32 v5, 1.0, v5
	v_cndmask_b32_e64 v6, 0, 32, vcc
	v_ldexp_f32 v3, v3, v6
	v_log_f32_e32 v3, v3
	v_rcp_f32_e32 v5, v5
	v_mul_f32_e32 v6, 0x3f317217, v3
	v_fma_f32 v6, v3, s49, -v6
	v_fmac_f32_e32 v6, 0x3377d1cf, v3
	v_fmac_f32_e32 v6, 0x3f317217, v3
	v_cmp_lt_f32_e64 s[0:1], |v3|, s69
	v_fmac_f32_e32 v17, v5, v140
	v_max_f32_e32 v5, 0xda24260, v17
	v_cndmask_b32_e64 v3, v3, v6, s[0:1]
	v_cndmask_b32_e32 v6, 0, v231, vcc
	v_cmp_gt_f32_e32 vcc, s47, v4
	v_sub_f32_e32 v3, v3, v6
	s_nop 0
	v_cndmask_b32_e64 v6, 0, 32, vcc
	v_ldexp_f32 v4, v4, v6
	v_log_f32_e32 v4, v4
	s_nop 0
	v_mul_f32_e32 v6, 0x3f317217, v4
	v_fma_f32 v6, v4, s49, -v6
	v_fmac_f32_e32 v6, 0x3377d1cf, v4
	v_fmac_f32_e32 v6, 0x3f317217, v4
	v_cmp_lt_f32_e64 s[0:1], |v4|, s69
	s_nop 1
	v_cndmask_b32_e64 v4, v4, v6, s[0:1]
	v_cndmask_b32_e32 v6, 0, v231, vcc
	v_cmp_gt_f32_e32 vcc, s47, v5
	v_sub_f32_e32 v4, v4, v6
	s_nop 0
	v_cndmask_b32_e64 v6, 0, 32, vcc
	v_ldexp_f32 v5, v5, v6
	v_log_f32_e32 v5, v5
	s_nop 0
	v_mul_f32_e32 v6, 0x3f317217, v5
	v_fma_f32 v6, v5, s49, -v6
	v_fmac_f32_e32 v6, 0x3377d1cf, v5
	v_fmac_f32_e32 v6, 0x3f317217, v5
	v_cmp_lt_f32_e64 s[0:1], |v5|, s69
	s_nop 1
	v_cndmask_b32_e64 v5, v5, v6, s[0:1]
	v_cndmask_b32_e32 v6, 0, v231, vcc
	v_sub_f32_e32 v5, v5, v6
	flat_store_dwordx4 v[30:31], v[2:5] offset:576 nt
	s_andn2_b64 vcc, exec, s[36:37]
	s_mov_b64 s[0:1], -1
	s_cbranch_vccnz .LBB0_651
	s_branch .LBB0_779

; __device__ __forceinline__ float sigmoid_fast(float x) { return __builtin_amdgcn_rcpf(1.0f + __expf(-x)); }
;     __device__ __forceinline__ void operator()(EPI_SIG) const {
;     ...
;             for (int m = 0; m < 4; ++m) { float* rowp = C + (size_t)(row0 + ai * 128 + m * 16) * NZF + u.pn * 256 + cc;
; #pragma unroll
;                 for (int bj = 0; bj < 2; ++bj)
; #pragma unroll
;                     for (int n = 0; n < 2; ++n) { f32x4 v = acc[ai][bj][m][n];
;                         if (u.pn < 2) {
; #pragma unroll
;                             for (int t = 0; t < 4; ++t) v[t] = __logf(fmaxf(lbv[bj][n][t] + (1.0f - lbv[bj][n][t]) * sigmoid_fast(v[t]), 1e-30f)); }
;                         if (u.pn < 2 || (bj == 0 && wc == 0 && (n == 0 || fq < 2))) *(f32x4*)(rowp + bj * 128 + n * 16) = v; } }
.LBB0_741:
	flat_store_dwordx4 v[132:133], v[124:127] offset:64 nt
	s_or_b64 exec, exec, s[2:3]
	s_and_b64 vcc, exec, s[0:1]
	s_cbranch_vccz .LBB0_687

; __device__ __forceinline__ float sigmoid_fast(float x) { return __builtin_amdgcn_rcpf(1.0f + __expf(-x)); }
;     __device__ __forceinline__ void operator()(EPI_SIG) const {
;     ...
;             for (int m = 0; m < 4; ++m) { float* rowp = C + (size_t)(row0 + ai * 128 + m * 16) * NZF + u.pn * 256 + cc;
; #pragma unroll
;                 for (int bj = 0; bj < 2; ++bj)
; #pragma unroll
;                     for (int n = 0; n < 2; ++n) { f32x4 v = acc[ai][bj][m][n];
;                         if (u.pn < 2) {
; #pragma unroll
;                             for (int t = 0; t < 4; ++t) v[t] = __logf(fmaxf(lbv[bj][n][t] + (1.0f - lbv[bj][n][t]) * sigmoid_fast(v[t]), 1e-30f)); }
;                         if (u.pn < 2 || (bj == 0 && wc == 0 && (n == 0 || fq < 2))) *(f32x4*)(rowp + bj * 128 + n * 16) = v; } }
.LBB0_747:
	flat_store_dwordx4 v[116:117], v[108:111] offset:64 nt
	s_or_b64 exec, exec, s[2:3]
	s_and_b64 vcc, exec, s[0:1]
	s_cbranch_vccz .LBB0_695

; __device__ __forceinline__ float sigmoid_fast(float x) { return __builtin_amdgcn_rcpf(1.0f + __expf(-x)); }
;     __device__ __forceinline__ void operator()(EPI_SIG) const {
;     ...
;             for (int m = 0; m < 4; ++m) { float* rowp = C + (size_t)(row0 + ai * 128 + m * 16) * NZF + u.pn * 256 + cc;
; #pragma unroll
;                 for (int bj = 0; bj < 2; ++bj)
; #pragma unroll
;                     for (int n = 0; n < 2; ++n) { f32x4 v = acc[ai][bj][m][n];
;                         if (u.pn < 2) {
; #pragma unroll
;                             for (int t = 0; t < 4; ++t) v[t] = __logf(fmaxf(lbv[bj][n][t] + (1.0f - lbv[bj][n][t]) * sigmoid_fast(v[t]), 1e-30f)); }
;                         if (u.pn < 2 || (bj == 0 && wc == 0 && (n == 0 || fq < 2))) *(f32x4*)(rowp + bj * 128 + n * 16) = v; } }
.LBB0_753:
	flat_store_dwordx4 v[100:101], v[92:95] offset:64 nt
	s_or_b64 exec, exec, s[2:3]
	s_and_b64 vcc, exec, s[0:1]
	s_cbranch_vccz .LBB0_703

; __device__ __forceinline__ float sigmoid_fast(float x) { return __builtin_amdgcn_rcpf(1.0f + __expf(-x)); }
;     __device__ __forceinline__ void operator()(EPI_SIG) const {
;     ...
;             for (int m = 0; m < 4; ++m) { float* rowp = C + (size_t)(row0 + ai * 128 + m * 16) * NZF + u.pn * 256 + cc;
; #pragma unroll
;                 for (int bj = 0; bj < 2; ++bj)
; #pragma unroll
;                     for (int n = 0; n < 2; ++n) { f32x4 v = acc[ai][bj][m][n];
;                         if (u.pn < 2) {
; #pragma unroll
;                             for (int t = 0; t < 4; ++t) v[t] = __logf(fmaxf(lbv[bj][n][t] + (1.0f - lbv[bj][n][t]) * sigmoid_fast(v[t]), 1e-30f)); }
;                         if (u.pn < 2 || (bj == 0 && wc == 0 && (n == 0 || fq < 2))) *(f32x4*)(rowp + bj * 128 + n * 16) = v; } }
.LBB0_759:
	flat_store_dwordx4 v[84:85], v[76:79] offset:64 nt
	s_or_b64 exec, exec, s[2:3]
	s_and_b64 vcc, exec, s[0:1]
	s_cbranch_vccz .LBB0_711

; __device__ __forceinline__ float sigmoid_fast(float x) { return __builtin_amdgcn_rcpf(1.0f + __expf(-x)); }
;     __device__ __forceinline__ void operator()(EPI_SIG) const {
;     ...
;             for (int m = 0; m < 4; ++m) { float* rowp = C + (size_t)(row0 + ai * 128 + m * 16) * NZF + u.pn * 256 + cc;
; #pragma unroll
;                 for (int bj = 0; bj < 2; ++bj)
; #pragma unroll
;                     for (int n = 0; n < 2; ++n) { f32x4 v = acc[ai][bj][m][n];
;                         if (u.pn < 2) {
; #pragma unroll
;                             for (int t = 0; t < 4; ++t) v[t] = __logf(fmaxf(lbv[bj][n][t] + (1.0f - lbv[bj][n][t]) * sigmoid_fast(v[t]), 1e-30f)); }
;                         if (u.pn < 2 || (bj == 0 && wc == 0 && (n == 0 || fq < 2))) *(f32x4*)(rowp + bj * 128 + n * 16) = v; } }
.LBB0_765:
	flat_store_dwordx4 v[68:69], v[60:63] offset:64 nt
	s_or_b64 exec, exec, s[2:3]
	s_and_b64 vcc, exec, s[0:1]
	s_cbranch_vccz .LBB0_719

; __device__ __forceinline__ float sigmoid_fast(float x) { return __builtin_amdgcn_rcpf(1.0f + __expf(-x)); }
;     __device__ __forceinline__ void operator()(EPI_SIG) const {
;     ...
;             for (int m = 0; m < 4; ++m) { float* rowp = C + (size_t)(row0 + ai * 128 + m * 16) * NZF + u.pn * 256 + cc;
; #pragma unroll
;                 for (int bj = 0; bj < 2; ++bj)
; #pragma unroll
;                     for (int n = 0; n < 2; ++n) { f32x4 v = acc[ai][bj][m][n];
;                         if (u.pn < 2) {
; #pragma unroll
;                             for (int t = 0; t < 4; ++t) v[t] = __logf(fmaxf(lbv[bj][n][t] + (1.0f - lbv[bj][n][t]) * sigmoid_fast(v[t]), 1e-30f)); }
;                         if (u.pn < 2 || (bj == 0 && wc == 0 && (n == 0 || fq < 2))) *(f32x4*)(rowp + bj * 128 + n * 16) = v; } }
.LBB0_771:
	flat_store_dwordx4 v[52:53], v[42:45] offset:64 nt
	s_or_b64 exec, exec, s[2:3]
	s_and_b64 vcc, exec, s[0:1]
	s_cbranch_vccz .LBB0_727

; __device__ __forceinline__ float sigmoid_fast(float x) { return __builtin_amdgcn_rcpf(1.0f + __expf(-x)); }
;     __device__ __forceinline__ void operator()(EPI_SIG) const {
;     ...
;             for (int m = 0; m < 4; ++m) { float* rowp = C + (size_t)(row0 + ai * 128 + m * 16) * NZF + u.pn * 256 + cc;
; #pragma unroll
;                 for (int bj = 0; bj < 2; ++bj)
; #pragma unroll
;                     for (int n = 0; n < 2; ++n) { f32x4 v = acc[ai][bj][m][n];
;                         if (u.pn < 2) {
; #pragma unroll
;                             for (int t = 0; t < 4; ++t) v[t] = __logf(fmaxf(lbv[bj][n][t] + (1.0f - lbv[bj][n][t]) * sigmoid_fast(v[t]), 1e-30f)); }
;                         if (u.pn < 2 || (bj == 0 && wc == 0 && (n == 0 || fq < 2))) *(f32x4*)(rowp + bj * 128 + n * 16) = v; } }
.LBB0_777:
	flat_store_dwordx4 v[30:31], v[10:13] offset:64 nt
	s_or_b64 exec, exec, s[2:3]
	s_and_b64 vcc, exec, s[0:1]
	s_cbranch_vccz .LBB0_735
